# P7 sample-row GEMM K loop: register-staged prefetch (loads to VGPRs 5 K steps ahead, ds_write into a 2-slot LDS ring with the DMA's image), fully unrolled
# baseline (speedup 1.0000x reference)
.LBB0_841:
	s_lshl_b32 s50, s1, 7
	s_ashr_i32 s51, s50, 31
	s_lshl_b64 s[10:11], s[50:51], 12
	s_add_u32 s54, s78, s10
	v_readfirstlane_b32 s8, v0
	s_addc_u32 s55, s79, s11
	s_lshl_b32 s3, s8, 4
	s_and_b32 s3, s3, 0xfffffc00
	s_add_i32 s3, s3, 0
	s_lshr_b32 s51, s3, 10
	s_and_b32 s52, s51, 3
	s_lshr_b32 s53, s51, 2
	v_and_b32_e32 v107, 63, v0
	v_lshl_add_u32 v204, v107, 4, s3
	s_lshl_b32 s53, s53, 13
	v_add_u32_e32 v205, s53, v60
	s_lshl_b32 s52, s52, 12
	s_add_i32 s52, s52, 0x4000
	v_add_u32_e32 v106, s52, v58
	v_mov_b32_e32 v2, 0
	v_mov_b32_e32 v3, 0
	v_mov_b32_e32 v4, 0
	v_mov_b32_e32 v5, 0
	v_mov_b32_e32 v6, 0
	v_mov_b32_e32 v7, 0
	v_mov_b32_e32 v8, 0
	v_mov_b32_e32 v9, 0
	v_mov_b32_e32 v10, 0
	v_mov_b32_e32 v11, 0
	v_mov_b32_e32 v12, 0
	v_mov_b32_e32 v13, 0
	v_mov_b32_e32 v14, 0
	v_mov_b32_e32 v15, 0
	v_mov_b32_e32 v16, 0
	v_mov_b32_e32 v17, 0
	v_mov_b32_e32 v18, 0
	v_mov_b32_e32 v19, 0
	v_mov_b32_e32 v20, 0
	v_mov_b32_e32 v21, 0
	v_mov_b32_e32 v22, 0
	v_mov_b32_e32 v23, 0
	v_mov_b32_e32 v24, 0
	v_mov_b32_e32 v25, 0
	v_mov_b32_e32 v26, 0
	v_mov_b32_e32 v27, 0
	v_mov_b32_e32 v28, 0
	v_mov_b32_e32 v29, 0
	v_mov_b32_e32 v30, 0
	v_mov_b32_e32 v31, 0
	v_mov_b32_e32 v32, 0
	v_mov_b32_e32 v33, 0
	s_add_u32 s60, s6, 0x0
	s_addc_u32 s61, s7, 0
	s_add_u32 s62, s54, 0x0
	s_addc_u32 s63, s55, 0
	global_load_dwordx4 v[54:57], v150, s[60:61]
	global_load_dwordx4 v[62:65], v150, s[62:63]
	global_load_dwordx4 v[66:69], v152, s[60:61]
	global_load_dwordx4 v[70:73], v152, s[62:63]
	s_add_u32 s60, s6, 0x80
	s_addc_u32 s61, s7, 0
	s_add_u32 s62, s54, 0x80
	s_addc_u32 s63, s55, 0
	global_load_dwordx4 v[74:77], v150, s[60:61]
	global_load_dwordx4 v[78:81], v150, s[62:63]
	global_load_dwordx4 v[82:85], v152, s[60:61]
	global_load_dwordx4 v[86:89], v152, s[62:63]
	s_add_u32 s60, s6, 0x100
	s_addc_u32 s61, s7, 0
	s_add_u32 s62, s54, 0x100
	s_addc_u32 s63, s55, 0
	global_load_dwordx4 v[90:93], v150, s[60:61]
	global_load_dwordx4 v[94:97], v150, s[62:63]
	global_load_dwordx4 v[98:101], v152, s[60:61]
	global_load_dwordx4 v[102:105], v152, s[62:63]
	s_add_u32 s60, s6, 0x180
	s_addc_u32 s61, s7, 0
	s_add_u32 s62, s54, 0x180
	s_addc_u32 s63, s55, 0
	global_load_dwordx4 v[136:139], v150, s[60:61]
	global_load_dwordx4 v[140:143], v150, s[62:63]
	global_load_dwordx4 v[144:147], v152, s[60:61]
	global_load_dwordx4 v[154:157], v152, s[62:63]
	s_add_u32 s60, s6, 0x200
	s_addc_u32 s61, s7, 0
	s_add_u32 s62, s54, 0x200
	s_addc_u32 s63, s55, 0
	global_load_dwordx4 v[158:161], v150, s[60:61]
	global_load_dwordx4 v[162:165], v150, s[62:63]
	global_load_dwordx4 v[166:169], v152, s[60:61]
	global_load_dwordx4 v[176:179], v152, s[62:63]
	s_waitcnt vmcnt(16)
	ds_write_b128 v204, v[54:57] offset:0
	ds_write_b128 v204, v[62:65] offset:16384
	ds_write_b128 v204, v[66:69] offset:8192
	ds_write_b128 v204, v[70:73] offset:24576
	s_add_u32 s60, s6, 0x280
	s_addc_u32 s61, s7, 0
	s_add_u32 s62, s54, 0x280
	s_addc_u32 s63, s55, 0
	global_load_dwordx4 v[54:57], v150, s[60:61]
	global_load_dwordx4 v[62:65], v150, s[62:63]
	global_load_dwordx4 v[66:69], v152, s[60:61]
	global_load_dwordx4 v[70:73], v152, s[62:63]
	s_waitcnt lgkmcnt(0)
	s_barrier
	ds_read_b128 v[244:247], v106 offset:0
	ds_read_b128 v[248:251], v106 offset:1024
	ds_read_b128 v[180:183], v106 offset:2048
	ds_read_b128 v[184:187], v106 offset:3072
	ds_read_b128 v[212:215], v205 offset:0
	ds_read_b128 v[216:219], v205 offset:1024
	ds_read_b128 v[220:223], v205 offset:2048
	ds_read_b128 v[224:227], v205 offset:3072
	ds_read_b128 v[228:231], v205 offset:4096
	ds_read_b128 v[232:235], v205 offset:5120
	ds_read_b128 v[236:239], v205 offset:6144
	ds_read_b128 v[240:243], v205 offset:7168
	s_waitcnt lgkmcnt(0)
	v_mfma_f32_16x16x32_bf16 v[30:33], v[244:247], v[212:215], v[30:33]
	v_mfma_f32_16x16x32_bf16 v[26:29], v[180:183], v[212:215], v[26:29]
	v_mfma_f32_16x16x32_bf16 v[22:25], v[244:247], v[220:223], v[22:25]
	v_mfma_f32_16x16x32_bf16 v[18:21], v[180:183], v[220:223], v[18:21]
	v_mfma_f32_16x16x32_bf16 v[14:17], v[244:247], v[228:231], v[14:17]
	v_mfma_f32_16x16x32_bf16 v[10:13], v[180:183], v[228:231], v[10:13]
	v_mfma_f32_16x16x32_bf16 v[6:9], v[244:247], v[236:239], v[6:9]
	v_mfma_f32_16x16x32_bf16 v[2:5], v[180:183], v[236:239], v[2:5]
	v_mfma_f32_16x16x32_bf16 v[30:33], v[248:251], v[216:219], v[30:33]
	v_mfma_f32_16x16x32_bf16 v[26:29], v[184:187], v[216:219], v[26:29]
	v_mfma_f32_16x16x32_bf16 v[22:25], v[248:251], v[224:227], v[22:25]
	v_mfma_f32_16x16x32_bf16 v[18:21], v[184:187], v[224:227], v[18:21]
	v_mfma_f32_16x16x32_bf16 v[14:17], v[248:251], v[232:235], v[14:17]
	v_mfma_f32_16x16x32_bf16 v[10:13], v[184:187], v[232:235], v[10:13]
	v_mfma_f32_16x16x32_bf16 v[6:9], v[248:251], v[240:243], v[6:9]
	v_mfma_f32_16x16x32_bf16 v[2:5], v[184:187], v[240:243], v[2:5]
	s_waitcnt vmcnt(16)
	ds_write_b128 v204, v[74:77] offset:32768
	ds_write_b128 v204, v[78:81] offset:49152
	ds_write_b128 v204, v[82:85] offset:40960
	ds_write_b128 v204, v[86:89] offset:57344
	s_add_u32 s60, s6, 0x300
	s_addc_u32 s61, s7, 0
	s_add_u32 s62, s54, 0x300
	s_addc_u32 s63, s55, 0
	global_load_dwordx4 v[74:77], v150, s[60:61]
	global_load_dwordx4 v[78:81], v150, s[62:63]
	global_load_dwordx4 v[82:85], v152, s[60:61]
	global_load_dwordx4 v[86:89], v152, s[62:63]
	s_waitcnt lgkmcnt(0)
	s_barrier
	ds_read_b128 v[244:247], v106 offset:32768
	ds_read_b128 v[248:251], v106 offset:33792
	ds_read_b128 v[180:183], v106 offset:34816
	ds_read_b128 v[184:187], v106 offset:35840
	ds_read_b128 v[212:215], v205 offset:32768
	ds_read_b128 v[216:219], v205 offset:33792
	ds_read_b128 v[220:223], v205 offset:34816
	ds_read_b128 v[224:227], v205 offset:35840
	ds_read_b128 v[228:231], v205 offset:36864
	ds_read_b128 v[232:235], v205 offset:37888
	ds_read_b128 v[236:239], v205 offset:38912
	ds_read_b128 v[240:243], v205 offset:39936
	s_waitcnt lgkmcnt(0)
	v_mfma_f32_16x16x32_bf16 v[30:33], v[244:247], v[212:215], v[30:33]
	v_mfma_f32_16x16x32_bf16 v[26:29], v[180:183], v[212:215], v[26:29]
	v_mfma_f32_16x16x32_bf16 v[22:25], v[244:247], v[220:223], v[22:25]
	v_mfma_f32_16x16x32_bf16 v[18:21], v[180:183], v[220:223], v[18:21]
	v_mfma_f32_16x16x32_bf16 v[14:17], v[244:247], v[228:231], v[14:17]
	v_mfma_f32_16x16x32_bf16 v[10:13], v[180:183], v[228:231], v[10:13]
	v_mfma_f32_16x16x32_bf16 v[6:9], v[244:247], v[236:239], v[6:9]
	v_mfma_f32_16x16x32_bf16 v[2:5], v[180:183], v[236:239], v[2:5]
	v_mfma_f32_16x16x32_bf16 v[30:33], v[248:251], v[216:219], v[30:33]
	v_mfma_f32_16x16x32_bf16 v[26:29], v[184:187], v[216:219], v[26:29]
	v_mfma_f32_16x16x32_bf16 v[22:25], v[248:251], v[224:227], v[22:25]
	v_mfma_f32_16x16x32_bf16 v[18:21], v[184:187], v[224:227], v[18:21]
	v_mfma_f32_16x16x32_bf16 v[14:17], v[248:251], v[232:235], v[14:17]
	v_mfma_f32_16x16x32_bf16 v[10:13], v[184:187], v[232:235], v[10:13]
	v_mfma_f32_16x16x32_bf16 v[6:9], v[248:251], v[240:243], v[6:9]
	v_mfma_f32_16x16x32_bf16 v[2:5], v[184:187], v[240:243], v[2:5]
	s_waitcnt vmcnt(16)
	ds_write_b128 v204, v[90:93] offset:0
	ds_write_b128 v204, v[94:97] offset:16384
	ds_write_b128 v204, v[98:101] offset:8192
	ds_write_b128 v204, v[102:105] offset:24576
	s_add_u32 s60, s6, 0x380
	s_addc_u32 s61, s7, 0
	s_add_u32 s62, s54, 0x380
	s_addc_u32 s63, s55, 0
	global_load_dwordx4 v[90:93], v150, s[60:61]
	global_load_dwordx4 v[94:97], v150, s[62:63]
	global_load_dwordx4 v[98:101], v152, s[60:61]
	global_load_dwordx4 v[102:105], v152, s[62:63]
	s_waitcnt lgkmcnt(0)
	s_barrier
	ds_read_b128 v[244:247], v106 offset:0
	ds_read_b128 v[248:251], v106 offset:1024
	ds_read_b128 v[180:183], v106 offset:2048
	ds_read_b128 v[184:187], v106 offset:3072
	ds_read_b128 v[212:215], v205 offset:0
	ds_read_b128 v[216:219], v205 offset:1024
	ds_read_b128 v[220:223], v205 offset:2048
	ds_read_b128 v[224:227], v205 offset:3072
	ds_read_b128 v[228:231], v205 offset:4096
	ds_read_b128 v[232:235], v205 offset:5120
	ds_read_b128 v[236:239], v205 offset:6144
	ds_read_b128 v[240:243], v205 offset:7168
	s_waitcnt lgkmcnt(0)
	v_mfma_f32_16x16x32_bf16 v[30:33], v[244:247], v[212:215], v[30:33]
	v_mfma_f32_16x16x32_bf16 v[26:29], v[180:183], v[212:215], v[26:29]
	v_mfma_f32_16x16x32_bf16 v[22:25], v[244:247], v[220:223], v[22:25]
	v_mfma_f32_16x16x32_bf16 v[18:21], v[180:183], v[220:223], v[18:21]
	v_mfma_f32_16x16x32_bf16 v[14:17], v[244:247], v[228:231], v[14:17]
	v_mfma_f32_16x16x32_bf16 v[10:13], v[180:183], v[228:231], v[10:13]
	v_mfma_f32_16x16x32_bf16 v[6:9], v[244:247], v[236:239], v[6:9]
	v_mfma_f32_16x16x32_bf16 v[2:5], v[180:183], v[236:239], v[2:5]
	v_mfma_f32_16x16x32_bf16 v[30:33], v[248:251], v[216:219], v[30:33]
	v_mfma_f32_16x16x32_bf16 v[26:29], v[184:187], v[216:219], v[26:29]
	v_mfma_f32_16x16x32_bf16 v[22:25], v[248:251], v[224:227], v[22:25]
	v_mfma_f32_16x16x32_bf16 v[18:21], v[184:187], v[224:227], v[18:21]
	v_mfma_f32_16x16x32_bf16 v[14:17], v[248:251], v[232:235], v[14:17]
	v_mfma_f32_16x16x32_bf16 v[10:13], v[184:187], v[232:235], v[10:13]
	v_mfma_f32_16x16x32_bf16 v[6:9], v[248:251], v[240:243], v[6:9]
	v_mfma_f32_16x16x32_bf16 v[2:5], v[184:187], v[240:243], v[2:5]
	s_waitcnt vmcnt(16)
	ds_write_b128 v204, v[136:139] offset:32768
	ds_write_b128 v204, v[140:143] offset:49152
	ds_write_b128 v204, v[144:147] offset:40960
	ds_write_b128 v204, v[154:157] offset:57344
	s_add_u32 s60, s6, 0x400
	s_addc_u32 s61, s7, 0
	s_add_u32 s62, s54, 0x400
	s_addc_u32 s63, s55, 0
	global_load_dwordx4 v[136:139], v150, s[60:61]
	global_load_dwordx4 v[140:143], v150, s[62:63]
	global_load_dwordx4 v[144:147], v152, s[60:61]
	global_load_dwordx4 v[154:157], v152, s[62:63]
	s_waitcnt lgkmcnt(0)
	s_barrier
	ds_read_b128 v[244:247], v106 offset:32768
	ds_read_b128 v[248:251], v106 offset:33792
	ds_read_b128 v[180:183], v106 offset:34816
	ds_read_b128 v[184:187], v106 offset:35840
	ds_read_b128 v[212:215], v205 offset:32768
	ds_read_b128 v[216:219], v205 offset:33792
	ds_read_b128 v[220:223], v205 offset:34816
	ds_read_b128 v[224:227], v205 offset:35840
	ds_read_b128 v[228:231], v205 offset:36864
	ds_read_b128 v[232:235], v205 offset:37888
	ds_read_b128 v[236:239], v205 offset:38912
	ds_read_b128 v[240:243], v205 offset:39936
	s_waitcnt lgkmcnt(0)
	v_mfma_f32_16x16x32_bf16 v[30:33], v[244:247], v[212:215], v[30:33]
	v_mfma_f32_16x16x32_bf16 v[26:29], v[180:183], v[212:215], v[26:29]
	v_mfma_f32_16x16x32_bf16 v[22:25], v[244:247], v[220:223], v[22:25]
	v_mfma_f32_16x16x32_bf16 v[18:21], v[180:183], v[220:223], v[18:21]
	v_mfma_f32_16x16x32_bf16 v[14:17], v[244:247], v[228:231], v[14:17]
	v_mfma_f32_16x16x32_bf16 v[10:13], v[180:183], v[228:231], v[10:13]
	v_mfma_f32_16x16x32_bf16 v[6:9], v[244:247], v[236:239], v[6:9]
	v_mfma_f32_16x16x32_bf16 v[2:5], v[180:183], v[236:239], v[2:5]
	v_mfma_f32_16x16x32_bf16 v[30:33], v[248:251], v[216:219], v[30:33]
	v_mfma_f32_16x16x32_bf16 v[26:29], v[184:187], v[216:219], v[26:29]
	v_mfma_f32_16x16x32_bf16 v[22:25], v[248:251], v[224:227], v[22:25]
	v_mfma_f32_16x16x32_bf16 v[18:21], v[184:187], v[224:227], v[18:21]
	v_mfma_f32_16x16x32_bf16 v[14:17], v[248:251], v[232:235], v[14:17]
	v_mfma_f32_16x16x32_bf16 v[10:13], v[184:187], v[232:235], v[10:13]
	v_mfma_f32_16x16x32_bf16 v[6:9], v[248:251], v[240:243], v[6:9]
	v_mfma_f32_16x16x32_bf16 v[2:5], v[184:187], v[240:243], v[2:5]
	s_waitcnt vmcnt(16)
	ds_write_b128 v204, v[158:161] offset:0
	ds_write_b128 v204, v[162:165] offset:16384
	ds_write_b128 v204, v[166:169] offset:8192
	ds_write_b128 v204, v[176:179] offset:24576
	s_add_u32 s60, s6, 0x480
	s_addc_u32 s61, s7, 0
	s_add_u32 s62, s54, 0x480
	s_addc_u32 s63, s55, 0
	global_load_dwordx4 v[158:161], v150, s[60:61]
	global_load_dwordx4 v[162:165], v150, s[62:63]
	global_load_dwordx4 v[166:169], v152, s[60:61]
	global_load_dwordx4 v[176:179], v152, s[62:63]
	s_waitcnt lgkmcnt(0)
	s_barrier
	ds_read_b128 v[244:247], v106 offset:0
	ds_read_b128 v[248:251], v106 offset:1024
	ds_read_b128 v[180:183], v106 offset:2048
	ds_read_b128 v[184:187], v106 offset:3072
	ds_read_b128 v[212:215], v205 offset:0
	ds_read_b128 v[216:219], v205 offset:1024
	ds_read_b128 v[220:223], v205 offset:2048
	ds_read_b128 v[224:227], v205 offset:3072
	ds_read_b128 v[228:231], v205 offset:4096
	ds_read_b128 v[232:235], v205 offset:5120
	ds_read_b128 v[236:239], v205 offset:6144
	ds_read_b128 v[240:243], v205 offset:7168
	s_waitcnt lgkmcnt(0)
	v_mfma_f32_16x16x32_bf16 v[30:33], v[244:247], v[212:215], v[30:33]
	v_mfma_f32_16x16x32_bf16 v[26:29], v[180:183], v[212:215], v[26:29]
	v_mfma_f32_16x16x32_bf16 v[22:25], v[244:247], v[220:223], v[22:25]
	v_mfma_f32_16x16x32_bf16 v[18:21], v[180:183], v[220:223], v[18:21]
	v_mfma_f32_16x16x32_bf16 v[14:17], v[244:247], v[228:231], v[14:17]
	v_mfma_f32_16x16x32_bf16 v[10:13], v[180:183], v[228:231], v[10:13]
	v_mfma_f32_16x16x32_bf16 v[6:9], v[244:247], v[236:239], v[6:9]
	v_mfma_f32_16x16x32_bf16 v[2:5], v[180:183], v[236:239], v[2:5]
	v_mfma_f32_16x16x32_bf16 v[30:33], v[248:251], v[216:219], v[30:33]
	v_mfma_f32_16x16x32_bf16 v[26:29], v[184:187], v[216:219], v[26:29]
	v_mfma_f32_16x16x32_bf16 v[22:25], v[248:251], v[224:227], v[22:25]
	v_mfma_f32_16x16x32_bf16 v[18:21], v[184:187], v[224:227], v[18:21]
	v_mfma_f32_16x16x32_bf16 v[14:17], v[248:251], v[232:235], v[14:17]
	v_mfma_f32_16x16x32_bf16 v[10:13], v[184:187], v[232:235], v[10:13]
	v_mfma_f32_16x16x32_bf16 v[6:9], v[248:251], v[240:243], v[6:9]
	v_mfma_f32_16x16x32_bf16 v[2:5], v[184:187], v[240:243], v[2:5]
	s_waitcnt vmcnt(16)
	ds_write_b128 v204, v[54:57] offset:32768
	ds_write_b128 v204, v[62:65] offset:49152
	ds_write_b128 v204, v[66:69] offset:40960
	ds_write_b128 v204, v[70:73] offset:57344
	s_add_u32 s60, s6, 0x500
	s_addc_u32 s61, s7, 0
	s_add_u32 s62, s54, 0x500
	s_addc_u32 s63, s55, 0
	global_load_dwordx4 v[54:57], v150, s[60:61]
	global_load_dwordx4 v[62:65], v150, s[62:63]
	global_load_dwordx4 v[66:69], v152, s[60:61]
	global_load_dwordx4 v[70:73], v152, s[62:63]
	s_waitcnt lgkmcnt(0)
	s_barrier
	ds_read_b128 v[244:247], v106 offset:32768
	ds_read_b128 v[248:251], v106 offset:33792
	ds_read_b128 v[180:183], v106 offset:34816
	ds_read_b128 v[184:187], v106 offset:35840
	ds_read_b128 v[212:215], v205 offset:32768
	ds_read_b128 v[216:219], v205 offset:33792
	ds_read_b128 v[220:223], v205 offset:34816
	ds_read_b128 v[224:227], v205 offset:35840
	ds_read_b128 v[228:231], v205 offset:36864
	ds_read_b128 v[232:235], v205 offset:37888
	ds_read_b128 v[236:239], v205 offset:38912
	ds_read_b128 v[240:243], v205 offset:39936
	s_waitcnt lgkmcnt(0)
	v_mfma_f32_16x16x32_bf16 v[30:33], v[244:247], v[212:215], v[30:33]
	v_mfma_f32_16x16x32_bf16 v[26:29], v[180:183], v[212:215], v[26:29]
	v_mfma_f32_16x16x32_bf16 v[22:25], v[244:247], v[220:223], v[22:25]
	v_mfma_f32_16x16x32_bf16 v[18:21], v[180:183], v[220:223], v[18:21]
	v_mfma_f32_16x16x32_bf16 v[14:17], v[244:247], v[228:231], v[14:17]
	v_mfma_f32_16x16x32_bf16 v[10:13], v[180:183], v[228:231], v[10:13]
	v_mfma_f32_16x16x32_bf16 v[6:9], v[244:247], v[236:239], v[6:9]
	v_mfma_f32_16x16x32_bf16 v[2:5], v[180:183], v[236:239], v[2:5]
	v_mfma_f32_16x16x32_bf16 v[30:33], v[248:251], v[216:219], v[30:33]
	v_mfma_f32_16x16x32_bf16 v[26:29], v[184:187], v[216:219], v[26:29]
	v_mfma_f32_16x16x32_bf16 v[22:25], v[248:251], v[224:227], v[22:25]
	v_mfma_f32_16x16x32_bf16 v[18:21], v[184:187], v[224:227], v[18:21]
	v_mfma_f32_16x16x32_bf16 v[14:17], v[248:251], v[232:235], v[14:17]
	v_mfma_f32_16x16x32_bf16 v[10:13], v[184:187], v[232:235], v[10:13]
	v_mfma_f32_16x16x32_bf16 v[6:9], v[248:251], v[240:243], v[6:9]
	v_mfma_f32_16x16x32_bf16 v[2:5], v[184:187], v[240:243], v[2:5]
	s_waitcnt vmcnt(16)
	ds_write_b128 v204, v[74:77] offset:0
	ds_write_b128 v204, v[78:81] offset:16384
	ds_write_b128 v204, v[82:85] offset:8192
	ds_write_b128 v204, v[86:89] offset:24576
	s_add_u32 s60, s6, 0x580
	s_addc_u32 s61, s7, 0
	s_add_u32 s62, s54, 0x580
	s_addc_u32 s63, s55, 0
	global_load_dwordx4 v[74:77], v150, s[60:61]
	global_load_dwordx4 v[78:81], v150, s[62:63]
	global_load_dwordx4 v[82:85], v152, s[60:61]
	global_load_dwordx4 v[86:89], v152, s[62:63]
	s_waitcnt lgkmcnt(0)
	s_barrier
	ds_read_b128 v[244:247], v106 offset:0
	ds_read_b128 v[248:251], v106 offset:1024
	ds_read_b128 v[180:183], v106 offset:2048
	ds_read_b128 v[184:187], v106 offset:3072
	ds_read_b128 v[212:215], v205 offset:0
	ds_read_b128 v[216:219], v205 offset:1024
	ds_read_b128 v[220:223], v205 offset:2048
	ds_read_b128 v[224:227], v205 offset:3072
	ds_read_b128 v[228:231], v205 offset:4096
	ds_read_b128 v[232:235], v205 offset:5120
	ds_read_b128 v[236:239], v205 offset:6144
	ds_read_b128 v[240:243], v205 offset:7168
	s_waitcnt lgkmcnt(0)
	v_mfma_f32_16x16x32_bf16 v[30:33], v[244:247], v[212:215], v[30:33]
	v_mfma_f32_16x16x32_bf16 v[26:29], v[180:183], v[212:215], v[26:29]
	v_mfma_f32_16x16x32_bf16 v[22:25], v[244:247], v[220:223], v[22:25]
	v_mfma_f32_16x16x32_bf16 v[18:21], v[180:183], v[220:223], v[18:21]
	v_mfma_f32_16x16x32_bf16 v[14:17], v[244:247], v[228:231], v[14:17]
	v_mfma_f32_16x16x32_bf16 v[10:13], v[180:183], v[228:231], v[10:13]
	v_mfma_f32_16x16x32_bf16 v[6:9], v[244:247], v[236:239], v[6:9]
	v_mfma_f32_16x16x32_bf16 v[2:5], v[180:183], v[236:239], v[2:5]
	v_mfma_f32_16x16x32_bf16 v[30:33], v[248:251], v[216:219], v[30:33]
	v_mfma_f32_16x16x32_bf16 v[26:29], v[184:187], v[216:219], v[26:29]
	v_mfma_f32_16x16x32_bf16 v[22:25], v[248:251], v[224:227], v[22:25]
	v_mfma_f32_16x16x32_bf16 v[18:21], v[184:187], v[224:227], v[18:21]
	v_mfma_f32_16x16x32_bf16 v[14:17], v[248:251], v[232:235], v[14:17]
	v_mfma_f32_16x16x32_bf16 v[10:13], v[184:187], v[232:235], v[10:13]
	v_mfma_f32_16x16x32_bf16 v[6:9], v[248:251], v[240:243], v[6:9]
	v_mfma_f32_16x16x32_bf16 v[2:5], v[184:187], v[240:243], v[2:5]
	s_waitcnt vmcnt(16)
	ds_write_b128 v204, v[90:93] offset:32768
	ds_write_b128 v204, v[94:97] offset:49152
	ds_write_b128 v204, v[98:101] offset:40960
	ds_write_b128 v204, v[102:105] offset:57344
	s_add_u32 s60, s6, 0x600
	s_addc_u32 s61, s7, 0
	s_add_u32 s62, s54, 0x600
	s_addc_u32 s63, s55, 0
	global_load_dwordx4 v[90:93], v150, s[60:61]
	global_load_dwordx4 v[94:97], v150, s[62:63]
	global_load_dwordx4 v[98:101], v152, s[60:61]
	global_load_dwordx4 v[102:105], v152, s[62:63]
	s_waitcnt lgkmcnt(0)
	s_barrier
	ds_read_b128 v[244:247], v106 offset:32768
	ds_read_b128 v[248:251], v106 offset:33792
	ds_read_b128 v[180:183], v106 offset:34816
	ds_read_b128 v[184:187], v106 offset:35840
	ds_read_b128 v[212:215], v205 offset:32768
	ds_read_b128 v[216:219], v205 offset:33792
	ds_read_b128 v[220:223], v205 offset:34816
	ds_read_b128 v[224:227], v205 offset:35840
	ds_read_b128 v[228:231], v205 offset:36864
	ds_read_b128 v[232:235], v205 offset:37888
	ds_read_b128 v[236:239], v205 offset:38912
	ds_read_b128 v[240:243], v205 offset:39936
	s_waitcnt lgkmcnt(0)
	v_mfma_f32_16x16x32_bf16 v[30:33], v[244:247], v[212:215], v[30:33]
	v_mfma_f32_16x16x32_bf16 v[26:29], v[180:183], v[212:215], v[26:29]
	v_mfma_f32_16x16x32_bf16 v[22:25], v[244:247], v[220:223], v[22:25]
	v_mfma_f32_16x16x32_bf16 v[18:21], v[180:183], v[220:223], v[18:21]
	v_mfma_f32_16x16x32_bf16 v[14:17], v[244:247], v[228:231], v[14:17]
	v_mfma_f32_16x16x32_bf16 v[10:13], v[180:183], v[228:231], v[10:13]
	v_mfma_f32_16x16x32_bf16 v[6:9], v[244:247], v[236:239], v[6:9]
	v_mfma_f32_16x16x32_bf16 v[2:5], v[180:183], v[236:239], v[2:5]
	v_mfma_f32_16x16x32_bf16 v[30:33], v[248:251], v[216:219], v[30:33]
	v_mfma_f32_16x16x32_bf16 v[26:29], v[184:187], v[216:219], v[26:29]
	v_mfma_f32_16x16x32_bf16 v[22:25], v[248:251], v[224:227], v[22:25]
	v_mfma_f32_16x16x32_bf16 v[18:21], v[184:187], v[224:227], v[18:21]
	v_mfma_f32_16x16x32_bf16 v[14:17], v[248:251], v[232:235], v[14:17]
	v_mfma_f32_16x16x32_bf16 v[10:13], v[184:187], v[232:235], v[10:13]
	v_mfma_f32_16x16x32_bf16 v[6:9], v[248:251], v[240:243], v[6:9]
	v_mfma_f32_16x16x32_bf16 v[2:5], v[184:187], v[240:243], v[2:5]
	s_waitcnt vmcnt(16)
	ds_write_b128 v204, v[136:139] offset:0
	ds_write_b128 v204, v[140:143] offset:16384
	ds_write_b128 v204, v[144:147] offset:8192
	ds_write_b128 v204, v[154:157] offset:24576
	s_add_u32 s60, s6, 0x680
	s_addc_u32 s61, s7, 0
	s_add_u32 s62, s54, 0x680
	s_addc_u32 s63, s55, 0
	global_load_dwordx4 v[136:139], v150, s[60:61]
	global_load_dwordx4 v[140:143], v150, s[62:63]
	global_load_dwordx4 v[144:147], v152, s[60:61]
	global_load_dwordx4 v[154:157], v152, s[62:63]
	s_waitcnt lgkmcnt(0)
	s_barrier
	ds_read_b128 v[244:247], v106 offset:0
	ds_read_b128 v[248:251], v106 offset:1024
	ds_read_b128 v[180:183], v106 offset:2048
	ds_read_b128 v[184:187], v106 offset:3072
	ds_read_b128 v[212:215], v205 offset:0
	ds_read_b128 v[216:219], v205 offset:1024
	ds_read_b128 v[220:223], v205 offset:2048
	ds_read_b128 v[224:227], v205 offset:3072
	ds_read_b128 v[228:231], v205 offset:4096
	ds_read_b128 v[232:235], v205 offset:5120
	ds_read_b128 v[236:239], v205 offset:6144
	ds_read_b128 v[240:243], v205 offset:7168
	s_waitcnt lgkmcnt(0)
	v_mfma_f32_16x16x32_bf16 v[30:33], v[244:247], v[212:215], v[30:33]
	v_mfma_f32_16x16x32_bf16 v[26:29], v[180:183], v[212:215], v[26:29]
	v_mfma_f32_16x16x32_bf16 v[22:25], v[244:247], v[220:223], v[22:25]
	v_mfma_f32_16x16x32_bf16 v[18:21], v[180:183], v[220:223], v[18:21]
	v_mfma_f32_16x16x32_bf16 v[14:17], v[244:247], v[228:231], v[14:17]
	v_mfma_f32_16x16x32_bf16 v[10:13], v[180:183], v[228:231], v[10:13]
	v_mfma_f32_16x16x32_bf16 v[6:9], v[244:247], v[236:239], v[6:9]
	v_mfma_f32_16x16x32_bf16 v[2:5], v[180:183], v[236:239], v[2:5]
	v_mfma_f32_16x16x32_bf16 v[30:33], v[248:251], v[216:219], v[30:33]
	v_mfma_f32_16x16x32_bf16 v[26:29], v[184:187], v[216:219], v[26:29]
	v_mfma_f32_16x16x32_bf16 v[22:25], v[248:251], v[224:227], v[22:25]
	v_mfma_f32_16x16x32_bf16 v[18:21], v[184:187], v[224:227], v[18:21]
	v_mfma_f32_16x16x32_bf16 v[14:17], v[248:251], v[232:235], v[14:17]
	v_mfma_f32_16x16x32_bf16 v[10:13], v[184:187], v[232:235], v[10:13]
	v_mfma_f32_16x16x32_bf16 v[6:9], v[248:251], v[240:243], v[6:9]
	v_mfma_f32_16x16x32_bf16 v[2:5], v[184:187], v[240:243], v[2:5]
	s_waitcnt vmcnt(16)
	ds_write_b128 v204, v[158:161] offset:32768
	ds_write_b128 v204, v[162:165] offset:49152
	ds_write_b128 v204, v[166:169] offset:40960
	ds_write_b128 v204, v[176:179] offset:57344
	s_add_u32 s60, s6, 0x700
	s_addc_u32 s61, s7, 0
	s_add_u32 s62, s54, 0x700
	s_addc_u32 s63, s55, 0
	global_load_dwordx4 v[158:161], v150, s[60:61]
	global_load_dwordx4 v[162:165], v150, s[62:63]
	global_load_dwordx4 v[166:169], v152, s[60:61]
	global_load_dwordx4 v[176:179], v152, s[62:63]
	s_waitcnt lgkmcnt(0)
	s_barrier
	ds_read_b128 v[244:247], v106 offset:32768
	ds_read_b128 v[248:251], v106 offset:33792
	ds_read_b128 v[180:183], v106 offset:34816
	ds_read_b128 v[184:187], v106 offset:35840
	ds_read_b128 v[212:215], v205 offset:32768
	ds_read_b128 v[216:219], v205 offset:33792
	ds_read_b128 v[220:223], v205 offset:34816
	ds_read_b128 v[224:227], v205 offset:35840
	ds_read_b128 v[228:231], v205 offset:36864
	ds_read_b128 v[232:235], v205 offset:37888
	ds_read_b128 v[236:239], v205 offset:38912
	ds_read_b128 v[240:243], v205 offset:39936
	s_waitcnt lgkmcnt(0)
	v_mfma_f32_16x16x32_bf16 v[30:33], v[244:247], v[212:215], v[30:33]
	v_mfma_f32_16x16x32_bf16 v[26:29], v[180:183], v[212:215], v[26:29]
	v_mfma_f32_16x16x32_bf16 v[22:25], v[244:247], v[220:223], v[22:25]
	v_mfma_f32_16x16x32_bf16 v[18:21], v[180:183], v[220:223], v[18:21]
	v_mfma_f32_16x16x32_bf16 v[14:17], v[244:247], v[228:231], v[14:17]
	v_mfma_f32_16x16x32_bf16 v[10:13], v[180:183], v[228:231], v[10:13]
	v_mfma_f32_16x16x32_bf16 v[6:9], v[244:247], v[236:239], v[6:9]
	v_mfma_f32_16x16x32_bf16 v[2:5], v[180:183], v[236:239], v[2:5]
	v_mfma_f32_16x16x32_bf16 v[30:33], v[248:251], v[216:219], v[30:33]
	v_mfma_f32_16x16x32_bf16 v[26:29], v[184:187], v[216:219], v[26:29]
	v_mfma_f32_16x16x32_bf16 v[22:25], v[248:251], v[224:227], v[22:25]
	v_mfma_f32_16x16x32_bf16 v[18:21], v[184:187], v[224:227], v[18:21]
	v_mfma_f32_16x16x32_bf16 v[14:17], v[248:251], v[232:235], v[14:17]
	v_mfma_f32_16x16x32_bf16 v[10:13], v[184:187], v[232:235], v[10:13]
	v_mfma_f32_16x16x32_bf16 v[6:9], v[248:251], v[240:243], v[6:9]
	v_mfma_f32_16x16x32_bf16 v[2:5], v[184:187], v[240:243], v[2:5]
	s_waitcnt vmcnt(16)
	ds_write_b128 v204, v[54:57] offset:0
	ds_write_b128 v204, v[62:65] offset:16384
	ds_write_b128 v204, v[66:69] offset:8192
	ds_write_b128 v204, v[70:73] offset:24576
	s_add_u32 s60, s6, 0x780
	s_addc_u32 s61, s7, 0
	s_add_u32 s62, s54, 0x780
	s_addc_u32 s63, s55, 0
	global_load_dwordx4 v[54:57], v150, s[60:61]
	global_load_dwordx4 v[62:65], v150, s[62:63]
	global_load_dwordx4 v[66:69], v152, s[60:61]
	global_load_dwordx4 v[70:73], v152, s[62:63]
	s_waitcnt lgkmcnt(0)
	s_barrier
	ds_read_b128 v[244:247], v106 offset:0
	ds_read_b128 v[248:251], v106 offset:1024
	ds_read_b128 v[180:183], v106 offset:2048
	ds_read_b128 v[184:187], v106 offset:3072
	ds_read_b128 v[212:215], v205 offset:0
	ds_read_b128 v[216:219], v205 offset:1024
	ds_read_b128 v[220:223], v205 offset:2048
	ds_read_b128 v[224:227], v205 offset:3072
	ds_read_b128 v[228:231], v205 offset:4096
	ds_read_b128 v[232:235], v205 offset:5120
	ds_read_b128 v[236:239], v205 offset:6144
	ds_read_b128 v[240:243], v205 offset:7168
	s_waitcnt lgkmcnt(0)
	v_mfma_f32_16x16x32_bf16 v[30:33], v[244:247], v[212:215], v[30:33]
	v_mfma_f32_16x16x32_bf16 v[26:29], v[180:183], v[212:215], v[26:29]
	v_mfma_f32_16x16x32_bf16 v[22:25], v[244:247], v[220:223], v[22:25]
	v_mfma_f32_16x16x32_bf16 v[18:21], v[180:183], v[220:223], v[18:21]
	v_mfma_f32_16x16x32_bf16 v[14:17], v[244:247], v[228:231], v[14:17]
	v_mfma_f32_16x16x32_bf16 v[10:13], v[180:183], v[228:231], v[10:13]
	v_mfma_f32_16x16x32_bf16 v[6:9], v[244:247], v[236:239], v[6:9]
	v_mfma_f32_16x16x32_bf16 v[2:5], v[180:183], v[236:239], v[2:5]
	v_mfma_f32_16x16x32_bf16 v[30:33], v[248:251], v[216:219], v[30:33]
	v_mfma_f32_16x16x32_bf16 v[26:29], v[184:187], v[216:219], v[26:29]
	v_mfma_f32_16x16x32_bf16 v[22:25], v[248:251], v[224:227], v[22:25]
	v_mfma_f32_16x16x32_bf16 v[18:21], v[184:187], v[224:227], v[18:21]
	v_mfma_f32_16x16x32_bf16 v[14:17], v[248:251], v[232:235], v[14:17]
	v_mfma_f32_16x16x32_bf16 v[10:13], v[184:187], v[232:235], v[10:13]
	v_mfma_f32_16x16x32_bf16 v[6:9], v[248:251], v[240:243], v[6:9]
	v_mfma_f32_16x16x32_bf16 v[2:5], v[184:187], v[240:243], v[2:5]
	s_waitcnt vmcnt(16)
	ds_write_b128 v204, v[74:77] offset:32768
	ds_write_b128 v204, v[78:81] offset:49152
	ds_write_b128 v204, v[82:85] offset:40960
	ds_write_b128 v204, v[86:89] offset:57344
	s_add_u32 s60, s6, 0x800
	s_addc_u32 s61, s7, 0
	s_add_u32 s62, s54, 0x800
	s_addc_u32 s63, s55, 0
	global_load_dwordx4 v[74:77], v150, s[60:61]
	global_load_dwordx4 v[78:81], v150, s[62:63]
	global_load_dwordx4 v[82:85], v152, s[60:61]
	global_load_dwordx4 v[86:89], v152, s[62:63]
	s_waitcnt lgkmcnt(0)
	s_barrier
	ds_read_b128 v[244:247], v106 offset:32768
	ds_read_b128 v[248:251], v106 offset:33792
	ds_read_b128 v[180:183], v106 offset:34816
	ds_read_b128 v[184:187], v106 offset:35840
	ds_read_b128 v[212:215], v205 offset:32768
	ds_read_b128 v[216:219], v205 offset:33792
	ds_read_b128 v[220:223], v205 offset:34816
	ds_read_b128 v[224:227], v205 offset:35840
	ds_read_b128 v[228:231], v205 offset:36864
	ds_read_b128 v[232:235], v205 offset:37888
	ds_read_b128 v[236:239], v205 offset:38912
	ds_read_b128 v[240:243], v205 offset:39936
	s_waitcnt lgkmcnt(0)
	v_mfma_f32_16x16x32_bf16 v[30:33], v[244:247], v[212:215], v[30:33]
	v_mfma_f32_16x16x32_bf16 v[26:29], v[180:183], v[212:215], v[26:29]
	v_mfma_f32_16x16x32_bf16 v[22:25], v[244:247], v[220:223], v[22:25]
	v_mfma_f32_16x16x32_bf16 v[18:21], v[180:183], v[220:223], v[18:21]
	v_mfma_f32_16x16x32_bf16 v[14:17], v[244:247], v[228:231], v[14:17]
	v_mfma_f32_16x16x32_bf16 v[10:13], v[180:183], v[228:231], v[10:13]
	v_mfma_f32_16x16x32_bf16 v[6:9], v[244:247], v[236:239], v[6:9]
	v_mfma_f32_16x16x32_bf16 v[2:5], v[180:183], v[236:239], v[2:5]
	v_mfma_f32_16x16x32_bf16 v[30:33], v[248:251], v[216:219], v[30:33]
	v_mfma_f32_16x16x32_bf16 v[26:29], v[184:187], v[216:219], v[26:29]
	v_mfma_f32_16x16x32_bf16 v[22:25], v[248:251], v[224:227], v[22:25]
	v_mfma_f32_16x16x32_bf16 v[18:21], v[184:187], v[224:227], v[18:21]
	v_mfma_f32_16x16x32_bf16 v[14:17], v[248:251], v[232:235], v[14:17]
	v_mfma_f32_16x16x32_bf16 v[10:13], v[184:187], v[232:235], v[10:13]
	v_mfma_f32_16x16x32_bf16 v[6:9], v[248:251], v[240:243], v[6:9]
	v_mfma_f32_16x16x32_bf16 v[2:5], v[184:187], v[240:243], v[2:5]
	s_waitcnt vmcnt(16)
	ds_write_b128 v204, v[90:93] offset:0
	ds_write_b128 v204, v[94:97] offset:16384
	ds_write_b128 v204, v[98:101] offset:8192
	ds_write_b128 v204, v[102:105] offset:24576
	s_add_u32 s60, s6, 0x880
	s_addc_u32 s61, s7, 0
	s_add_u32 s62, s54, 0x880
	s_addc_u32 s63, s55, 0
	global_load_dwordx4 v[90:93], v150, s[60:61]
	global_load_dwordx4 v[94:97], v150, s[62:63]
	global_load_dwordx4 v[98:101], v152, s[60:61]
	global_load_dwordx4 v[102:105], v152, s[62:63]
	s_waitcnt lgkmcnt(0)
	s_barrier
	ds_read_b128 v[244:247], v106 offset:0
	ds_read_b128 v[248:251], v106 offset:1024
	ds_read_b128 v[180:183], v106 offset:2048
	ds_read_b128 v[184:187], v106 offset:3072
	ds_read_b128 v[212:215], v205 offset:0
	ds_read_b128 v[216:219], v205 offset:1024
	ds_read_b128 v[220:223], v205 offset:2048
	ds_read_b128 v[224:227], v205 offset:3072
	ds_read_b128 v[228:231], v205 offset:4096
	ds_read_b128 v[232:235], v205 offset:5120
	ds_read_b128 v[236:239], v205 offset:6144
	ds_read_b128 v[240:243], v205 offset:7168
	s_waitcnt lgkmcnt(0)
	v_mfma_f32_16x16x32_bf16 v[30:33], v[244:247], v[212:215], v[30:33]
	v_mfma_f32_16x16x32_bf16 v[26:29], v[180:183], v[212:215], v[26:29]
	v_mfma_f32_16x16x32_bf16 v[22:25], v[244:247], v[220:223], v[22:25]
	v_mfma_f32_16x16x32_bf16 v[18:21], v[180:183], v[220:223], v[18:21]
	v_mfma_f32_16x16x32_bf16 v[14:17], v[244:247], v[228:231], v[14:17]
	v_mfma_f32_16x16x32_bf16 v[10:13], v[180:183], v[228:231], v[10:13]
	v_mfma_f32_16x16x32_bf16 v[6:9], v[244:247], v[236:239], v[6:9]
	v_mfma_f32_16x16x32_bf16 v[2:5], v[180:183], v[236:239], v[2:5]
	v_mfma_f32_16x16x32_bf16 v[30:33], v[248:251], v[216:219], v[30:33]
	v_mfma_f32_16x16x32_bf16 v[26:29], v[184:187], v[216:219], v[26:29]
	v_mfma_f32_16x16x32_bf16 v[22:25], v[248:251], v[224:227], v[22:25]
	v_mfma_f32_16x16x32_bf16 v[18:21], v[184:187], v[224:227], v[18:21]
	v_mfma_f32_16x16x32_bf16 v[14:17], v[248:251], v[232:235], v[14:17]
	v_mfma_f32_16x16x32_bf16 v[10:13], v[184:187], v[232:235], v[10:13]
	v_mfma_f32_16x16x32_bf16 v[6:9], v[248:251], v[240:243], v[6:9]
	v_mfma_f32_16x16x32_bf16 v[2:5], v[184:187], v[240:243], v[2:5]
	s_waitcnt vmcnt(16)
	ds_write_b128 v204, v[136:139] offset:32768
	ds_write_b128 v204, v[140:143] offset:49152
	ds_write_b128 v204, v[144:147] offset:40960
	ds_write_b128 v204, v[154:157] offset:57344
	s_add_u32 s60, s6, 0x900
	s_addc_u32 s61, s7, 0
	s_add_u32 s62, s54, 0x900
	s_addc_u32 s63, s55, 0
	global_load_dwordx4 v[136:139], v150, s[60:61]
	global_load_dwordx4 v[140:143], v150, s[62:63]
	global_load_dwordx4 v[144:147], v152, s[60:61]
	global_load_dwordx4 v[154:157], v152, s[62:63]
	s_waitcnt lgkmcnt(0)
	s_barrier
	ds_read_b128 v[244:247], v106 offset:32768
	ds_read_b128 v[248:251], v106 offset:33792
	ds_read_b128 v[180:183], v106 offset:34816
	ds_read_b128 v[184:187], v106 offset:35840
	ds_read_b128 v[212:215], v205 offset:32768
	ds_read_b128 v[216:219], v205 offset:33792
	ds_read_b128 v[220:223], v205 offset:34816
	ds_read_b128 v[224:227], v205 offset:35840
	ds_read_b128 v[228:231], v205 offset:36864
	ds_read_b128 v[232:235], v205 offset:37888
	ds_read_b128 v[236:239], v205 offset:38912
	ds_read_b128 v[240:243], v205 offset:39936
	s_waitcnt lgkmcnt(0)
	v_mfma_f32_16x16x32_bf16 v[30:33], v[244:247], v[212:215], v[30:33]
	v_mfma_f32_16x16x32_bf16 v[26:29], v[180:183], v[212:215], v[26:29]
	v_mfma_f32_16x16x32_bf16 v[22:25], v[244:247], v[220:223], v[22:25]
	v_mfma_f32_16x16x32_bf16 v[18:21], v[180:183], v[220:223], v[18:21]
	v_mfma_f32_16x16x32_bf16 v[14:17], v[244:247], v[228:231], v[14:17]
	v_mfma_f32_16x16x32_bf16 v[10:13], v[180:183], v[228:231], v[10:13]
	v_mfma_f32_16x16x32_bf16 v[6:9], v[244:247], v[236:239], v[6:9]
	v_mfma_f32_16x16x32_bf16 v[2:5], v[180:183], v[236:239], v[2:5]
	v_mfma_f32_16x16x32_bf16 v[30:33], v[248:251], v[216:219], v[30:33]
	v_mfma_f32_16x16x32_bf16 v[26:29], v[184:187], v[216:219], v[26:29]
	v_mfma_f32_16x16x32_bf16 v[22:25], v[248:251], v[224:227], v[22:25]
	v_mfma_f32_16x16x32_bf16 v[18:21], v[184:187], v[224:227], v[18:21]
	v_mfma_f32_16x16x32_bf16 v[14:17], v[248:251], v[232:235], v[14:17]
	v_mfma_f32_16x16x32_bf16 v[10:13], v[184:187], v[232:235], v[10:13]
	v_mfma_f32_16x16x32_bf16 v[6:9], v[248:251], v[240:243], v[6:9]
	v_mfma_f32_16x16x32_bf16 v[2:5], v[184:187], v[240:243], v[2:5]
	s_waitcnt vmcnt(16)
	ds_write_b128 v204, v[158:161] offset:0
	ds_write_b128 v204, v[162:165] offset:16384
	ds_write_b128 v204, v[166:169] offset:8192
	ds_write_b128 v204, v[176:179] offset:24576
	s_add_u32 s60, s6, 0x980
	s_addc_u32 s61, s7, 0
	s_add_u32 s62, s54, 0x980
	s_addc_u32 s63, s55, 0
	global_load_dwordx4 v[158:161], v150, s[60:61]
	global_load_dwordx4 v[162:165], v150, s[62:63]
	global_load_dwordx4 v[166:169], v152, s[60:61]
	global_load_dwordx4 v[176:179], v152, s[62:63]
	s_waitcnt lgkmcnt(0)
	s_barrier
	ds_read_b128 v[244:247], v106 offset:0
	ds_read_b128 v[248:251], v106 offset:1024
	ds_read_b128 v[180:183], v106 offset:2048
	ds_read_b128 v[184:187], v106 offset:3072
	ds_read_b128 v[212:215], v205 offset:0
	ds_read_b128 v[216:219], v205 offset:1024
	ds_read_b128 v[220:223], v205 offset:2048
	ds_read_b128 v[224:227], v205 offset:3072
	ds_read_b128 v[228:231], v205 offset:4096
	ds_read_b128 v[232:235], v205 offset:5120
	ds_read_b128 v[236:239], v205 offset:6144
	ds_read_b128 v[240:243], v205 offset:7168
	s_waitcnt lgkmcnt(0)
	v_mfma_f32_16x16x32_bf16 v[30:33], v[244:247], v[212:215], v[30:33]
	v_mfma_f32_16x16x32_bf16 v[26:29], v[180:183], v[212:215], v[26:29]
	v_mfma_f32_16x16x32_bf16 v[22:25], v[244:247], v[220:223], v[22:25]
	v_mfma_f32_16x16x32_bf16 v[18:21], v[180:183], v[220:223], v[18:21]
	v_mfma_f32_16x16x32_bf16 v[14:17], v[244:247], v[228:231], v[14:17]
	v_mfma_f32_16x16x32_bf16 v[10:13], v[180:183], v[228:231], v[10:13]
	v_mfma_f32_16x16x32_bf16 v[6:9], v[244:247], v[236:239], v[6:9]
	v_mfma_f32_16x16x32_bf16 v[2:5], v[180:183], v[236:239], v[2:5]
	v_mfma_f32_16x16x32_bf16 v[30:33], v[248:251], v[216:219], v[30:33]
	v_mfma_f32_16x16x32_bf16 v[26:29], v[184:187], v[216:219], v[26:29]
	v_mfma_f32_16x16x32_bf16 v[22:25], v[248:251], v[224:227], v[22:25]
	v_mfma_f32_16x16x32_bf16 v[18:21], v[184:187], v[224:227], v[18:21]
	v_mfma_f32_16x16x32_bf16 v[14:17], v[248:251], v[232:235], v[14:17]
	v_mfma_f32_16x16x32_bf16 v[10:13], v[184:187], v[232:235], v[10:13]
	v_mfma_f32_16x16x32_bf16 v[6:9], v[248:251], v[240:243], v[6:9]
	v_mfma_f32_16x16x32_bf16 v[2:5], v[184:187], v[240:243], v[2:5]
	s_waitcnt vmcnt(16)
	ds_write_b128 v204, v[54:57] offset:32768
	ds_write_b128 v204, v[62:65] offset:49152
	ds_write_b128 v204, v[66:69] offset:40960
	ds_write_b128 v204, v[70:73] offset:57344
	s_add_u32 s60, s6, 0xa00
	s_addc_u32 s61, s7, 0
	s_add_u32 s62, s54, 0xa00
	s_addc_u32 s63, s55, 0
	global_load_dwordx4 v[54:57], v150, s[60:61]
	global_load_dwordx4 v[62:65], v150, s[62:63]
	global_load_dwordx4 v[66:69], v152, s[60:61]
	global_load_dwordx4 v[70:73], v152, s[62:63]
	s_waitcnt lgkmcnt(0)
	s_barrier
	ds_read_b128 v[244:247], v106 offset:32768
	ds_read_b128 v[248:251], v106 offset:33792
	ds_read_b128 v[180:183], v106 offset:34816
	ds_read_b128 v[184:187], v106 offset:35840
	ds_read_b128 v[212:215], v205 offset:32768
	ds_read_b128 v[216:219], v205 offset:33792
	ds_read_b128 v[220:223], v205 offset:34816
	ds_read_b128 v[224:227], v205 offset:35840
	ds_read_b128 v[228:231], v205 offset:36864
	ds_read_b128 v[232:235], v205 offset:37888
	ds_read_b128 v[236:239], v205 offset:38912
	ds_read_b128 v[240:243], v205 offset:39936
	s_waitcnt lgkmcnt(0)
	v_mfma_f32_16x16x32_bf16 v[30:33], v[244:247], v[212:215], v[30:33]
	v_mfma_f32_16x16x32_bf16 v[26:29], v[180:183], v[212:215], v[26:29]
	v_mfma_f32_16x16x32_bf16 v[22:25], v[244:247], v[220:223], v[22:25]
	v_mfma_f32_16x16x32_bf16 v[18:21], v[180:183], v[220:223], v[18:21]
	v_mfma_f32_16x16x32_bf16 v[14:17], v[244:247], v[228:231], v[14:17]
	v_mfma_f32_16x16x32_bf16 v[10:13], v[180:183], v[228:231], v[10:13]
	v_mfma_f32_16x16x32_bf16 v[6:9], v[244:247], v[236:239], v[6:9]
	v_mfma_f32_16x16x32_bf16 v[2:5], v[180:183], v[236:239], v[2:5]
	v_mfma_f32_16x16x32_bf16 v[30:33], v[248:251], v[216:219], v[30:33]
	v_mfma_f32_16x16x32_bf16 v[26:29], v[184:187], v[216:219], v[26:29]
	v_mfma_f32_16x16x32_bf16 v[22:25], v[248:251], v[224:227], v[22:25]
	v_mfma_f32_16x16x32_bf16 v[18:21], v[184:187], v[224:227], v[18:21]
	v_mfma_f32_16x16x32_bf16 v[14:17], v[248:251], v[232:235], v[14:17]
	v_mfma_f32_16x16x32_bf16 v[10:13], v[184:187], v[232:235], v[10:13]
	v_mfma_f32_16x16x32_bf16 v[6:9], v[248:251], v[240:243], v[6:9]
	v_mfma_f32_16x16x32_bf16 v[2:5], v[184:187], v[240:243], v[2:5]
	s_waitcnt vmcnt(16)
	ds_write_b128 v204, v[74:77] offset:0
	ds_write_b128 v204, v[78:81] offset:16384
	ds_write_b128 v204, v[82:85] offset:8192
	ds_write_b128 v204, v[86:89] offset:24576
	s_add_u32 s60, s6, 0xa80
	s_addc_u32 s61, s7, 0
	s_add_u32 s62, s54, 0xa80
	s_addc_u32 s63, s55, 0
	global_load_dwordx4 v[74:77], v150, s[60:61]
	global_load_dwordx4 v[78:81], v150, s[62:63]
	global_load_dwordx4 v[82:85], v152, s[60:61]
	global_load_dwordx4 v[86:89], v152, s[62:63]
	s_waitcnt lgkmcnt(0)
	s_barrier
	ds_read_b128 v[244:247], v106 offset:0
	ds_read_b128 v[248:251], v106 offset:1024
	ds_read_b128 v[180:183], v106 offset:2048
	ds_read_b128 v[184:187], v106 offset:3072
	ds_read_b128 v[212:215], v205 offset:0
	ds_read_b128 v[216:219], v205 offset:1024
	ds_read_b128 v[220:223], v205 offset:2048
	ds_read_b128 v[224:227], v205 offset:3072
	ds_read_b128 v[228:231], v205 offset:4096
	ds_read_b128 v[232:235], v205 offset:5120
	ds_read_b128 v[236:239], v205 offset:6144
	ds_read_b128 v[240:243], v205 offset:7168
	s_waitcnt lgkmcnt(0)
	v_mfma_f32_16x16x32_bf16 v[30:33], v[244:247], v[212:215], v[30:33]
	v_mfma_f32_16x16x32_bf16 v[26:29], v[180:183], v[212:215], v[26:29]
	v_mfma_f32_16x16x32_bf16 v[22:25], v[244:247], v[220:223], v[22:25]
	v_mfma_f32_16x16x32_bf16 v[18:21], v[180:183], v[220:223], v[18:21]
	v_mfma_f32_16x16x32_bf16 v[14:17], v[244:247], v[228:231], v[14:17]
	v_mfma_f32_16x16x32_bf16 v[10:13], v[180:183], v[228:231], v[10:13]
	v_mfma_f32_16x16x32_bf16 v[6:9], v[244:247], v[236:239], v[6:9]
	v_mfma_f32_16x16x32_bf16 v[2:5], v[180:183], v[236:239], v[2:5]
	v_mfma_f32_16x16x32_bf16 v[30:33], v[248:251], v[216:219], v[30:33]
	v_mfma_f32_16x16x32_bf16 v[26:29], v[184:187], v[216:219], v[26:29]
	v_mfma_f32_16x16x32_bf16 v[22:25], v[248:251], v[224:227], v[22:25]
	v_mfma_f32_16x16x32_bf16 v[18:21], v[184:187], v[224:227], v[18:21]
	v_mfma_f32_16x16x32_bf16 v[14:17], v[248:251], v[232:235], v[14:17]
	v_mfma_f32_16x16x32_bf16 v[10:13], v[184:187], v[232:235], v[10:13]
	v_mfma_f32_16x16x32_bf16 v[6:9], v[248:251], v[240:243], v[6:9]
	v_mfma_f32_16x16x32_bf16 v[2:5], v[184:187], v[240:243], v[2:5]
	s_waitcnt vmcnt(16)
	ds_write_b128 v204, v[90:93] offset:32768
	ds_write_b128 v204, v[94:97] offset:49152
	ds_write_b128 v204, v[98:101] offset:40960
	ds_write_b128 v204, v[102:105] offset:57344
	s_add_u32 s60, s6, 0xb00
	s_addc_u32 s61, s7, 0
	s_add_u32 s62, s54, 0xb00
	s_addc_u32 s63, s55, 0
	global_load_dwordx4 v[90:93], v150, s[60:61]
	global_load_dwordx4 v[94:97], v150, s[62:63]
	global_load_dwordx4 v[98:101], v152, s[60:61]
	global_load_dwordx4 v[102:105], v152, s[62:63]
	s_waitcnt lgkmcnt(0)
	s_barrier
	ds_read_b128 v[244:247], v106 offset:32768
	ds_read_b128 v[248:251], v106 offset:33792
	ds_read_b128 v[180:183], v106 offset:34816
	ds_read_b128 v[184:187], v106 offset:35840
	ds_read_b128 v[212:215], v205 offset:32768
	ds_read_b128 v[216:219], v205 offset:33792
	ds_read_b128 v[220:223], v205 offset:34816
	ds_read_b128 v[224:227], v205 offset:35840
	ds_read_b128 v[228:231], v205 offset:36864
	ds_read_b128 v[232:235], v205 offset:37888
	ds_read_b128 v[236:239], v205 offset:38912
	ds_read_b128 v[240:243], v205 offset:39936
	s_waitcnt lgkmcnt(0)
	v_mfma_f32_16x16x32_bf16 v[30:33], v[244:247], v[212:215], v[30:33]
	v_mfma_f32_16x16x32_bf16 v[26:29], v[180:183], v[212:215], v[26:29]
	v_mfma_f32_16x16x32_bf16 v[22:25], v[244:247], v[220:223], v[22:25]
	v_mfma_f32_16x16x32_bf16 v[18:21], v[180:183], v[220:223], v[18:21]
	v_mfma_f32_16x16x32_bf16 v[14:17], v[244:247], v[228:231], v[14:17]
	v_mfma_f32_16x16x32_bf16 v[10:13], v[180:183], v[228:231], v[10:13]
	v_mfma_f32_16x16x32_bf16 v[6:9], v[244:247], v[236:239], v[6:9]
	v_mfma_f32_16x16x32_bf16 v[2:5], v[180:183], v[236:239], v[2:5]
	v_mfma_f32_16x16x32_bf16 v[30:33], v[248:251], v[216:219], v[30:33]
	v_mfma_f32_16x16x32_bf16 v[26:29], v[184:187], v[216:219], v[26:29]
	v_mfma_f32_16x16x32_bf16 v[22:25], v[248:251], v[224:227], v[22:25]
	v_mfma_f32_16x16x32_bf16 v[18:21], v[184:187], v[224:227], v[18:21]
	v_mfma_f32_16x16x32_bf16 v[14:17], v[248:251], v[232:235], v[14:17]
	v_mfma_f32_16x16x32_bf16 v[10:13], v[184:187], v[232:235], v[10:13]
	v_mfma_f32_16x16x32_bf16 v[6:9], v[248:251], v[240:243], v[6:9]
	v_mfma_f32_16x16x32_bf16 v[2:5], v[184:187], v[240:243], v[2:5]
	s_waitcnt vmcnt(16)
	ds_write_b128 v204, v[136:139] offset:0
	ds_write_b128 v204, v[140:143] offset:16384
	ds_write_b128 v204, v[144:147] offset:8192
	ds_write_b128 v204, v[154:157] offset:24576
	s_add_u32 s60, s6, 0xb80
	s_addc_u32 s61, s7, 0
	s_add_u32 s62, s54, 0xb80
	s_addc_u32 s63, s55, 0
	global_load_dwordx4 v[136:139], v150, s[60:61]
	global_load_dwordx4 v[140:143], v150, s[62:63]
	global_load_dwordx4 v[144:147], v152, s[60:61]
	global_load_dwordx4 v[154:157], v152, s[62:63]
	s_waitcnt lgkmcnt(0)
	s_barrier
	ds_read_b128 v[244:247], v106 offset:0
	ds_read_b128 v[248:251], v106 offset:1024
	ds_read_b128 v[180:183], v106 offset:2048
	ds_read_b128 v[184:187], v106 offset:3072
	ds_read_b128 v[212:215], v205 offset:0
	ds_read_b128 v[216:219], v205 offset:1024
	ds_read_b128 v[220:223], v205 offset:2048
	ds_read_b128 v[224:227], v205 offset:3072
	ds_read_b128 v[228:231], v205 offset:4096
	ds_read_b128 v[232:235], v205 offset:5120
	ds_read_b128 v[236:239], v205 offset:6144
	ds_read_b128 v[240:243], v205 offset:7168
	s_waitcnt lgkmcnt(0)
	v_mfma_f32_16x16x32_bf16 v[30:33], v[244:247], v[212:215], v[30:33]
	v_mfma_f32_16x16x32_bf16 v[26:29], v[180:183], v[212:215], v[26:29]
	v_mfma_f32_16x16x32_bf16 v[22:25], v[244:247], v[220:223], v[22:25]
	v_mfma_f32_16x16x32_bf16 v[18:21], v[180:183], v[220:223], v[18:21]
	v_mfma_f32_16x16x32_bf16 v[14:17], v[244:247], v[228:231], v[14:17]
	v_mfma_f32_16x16x32_bf16 v[10:13], v[180:183], v[228:231], v[10:13]
	v_mfma_f32_16x16x32_bf16 v[6:9], v[244:247], v[236:239], v[6:9]
	v_mfma_f32_16x16x32_bf16 v[2:5], v[180:183], v[236:239], v[2:5]
	v_mfma_f32_16x16x32_bf16 v[30:33], v[248:251], v[216:219], v[30:33]
	v_mfma_f32_16x16x32_bf16 v[26:29], v[184:187], v[216:219], v[26:29]
	v_mfma_f32_16x16x32_bf16 v[22:25], v[248:251], v[224:227], v[22:25]
	v_mfma_f32_16x16x32_bf16 v[18:21], v[184:187], v[224:227], v[18:21]
	v_mfma_f32_16x16x32_bf16 v[14:17], v[248:251], v[232:235], v[14:17]
	v_mfma_f32_16x16x32_bf16 v[10:13], v[184:187], v[232:235], v[10:13]
	v_mfma_f32_16x16x32_bf16 v[6:9], v[248:251], v[240:243], v[6:9]
	v_mfma_f32_16x16x32_bf16 v[2:5], v[184:187], v[240:243], v[2:5]
	s_waitcnt vmcnt(16)
	ds_write_b128 v204, v[158:161] offset:32768
	ds_write_b128 v204, v[162:165] offset:49152
	ds_write_b128 v204, v[166:169] offset:40960
	ds_write_b128 v204, v[176:179] offset:57344
	s_add_u32 s60, s6, 0xc00
	s_addc_u32 s61, s7, 0
	s_add_u32 s62, s54, 0xc00
	s_addc_u32 s63, s55, 0
	global_load_dwordx4 v[158:161], v150, s[60:61]
	global_load_dwordx4 v[162:165], v150, s[62:63]
	global_load_dwordx4 v[166:169], v152, s[60:61]
	global_load_dwordx4 v[176:179], v152, s[62:63]
	s_waitcnt lgkmcnt(0)
	s_barrier
	ds_read_b128 v[244:247], v106 offset:32768
	ds_read_b128 v[248:251], v106 offset:33792
	ds_read_b128 v[180:183], v106 offset:34816
	ds_read_b128 v[184:187], v106 offset:35840
	ds_read_b128 v[212:215], v205 offset:32768
	ds_read_b128 v[216:219], v205 offset:33792
	ds_read_b128 v[220:223], v205 offset:34816
	ds_read_b128 v[224:227], v205 offset:35840
	ds_read_b128 v[228:231], v205 offset:36864
	ds_read_b128 v[232:235], v205 offset:37888
	ds_read_b128 v[236:239], v205 offset:38912
	ds_read_b128 v[240:243], v205 offset:39936
	s_waitcnt lgkmcnt(0)
	v_mfma_f32_16x16x32_bf16 v[30:33], v[244:247], v[212:215], v[30:33]
	v_mfma_f32_16x16x32_bf16 v[26:29], v[180:183], v[212:215], v[26:29]
	v_mfma_f32_16x16x32_bf16 v[22:25], v[244:247], v[220:223], v[22:25]
	v_mfma_f32_16x16x32_bf16 v[18:21], v[180:183], v[220:223], v[18:21]
	v_mfma_f32_16x16x32_bf16 v[14:17], v[244:247], v[228:231], v[14:17]
	v_mfma_f32_16x16x32_bf16 v[10:13], v[180:183], v[228:231], v[10:13]
	v_mfma_f32_16x16x32_bf16 v[6:9], v[244:247], v[236:239], v[6:9]
	v_mfma_f32_16x16x32_bf16 v[2:5], v[180:183], v[236:239], v[2:5]
	v_mfma_f32_16x16x32_bf16 v[30:33], v[248:251], v[216:219], v[30:33]
	v_mfma_f32_16x16x32_bf16 v[26:29], v[184:187], v[216:219], v[26:29]
	v_mfma_f32_16x16x32_bf16 v[22:25], v[248:251], v[224:227], v[22:25]
	v_mfma_f32_16x16x32_bf16 v[18:21], v[184:187], v[224:227], v[18:21]
	v_mfma_f32_16x16x32_bf16 v[14:17], v[248:251], v[232:235], v[14:17]
	v_mfma_f32_16x16x32_bf16 v[10:13], v[184:187], v[232:235], v[10:13]
	v_mfma_f32_16x16x32_bf16 v[6:9], v[248:251], v[240:243], v[6:9]
	v_mfma_f32_16x16x32_bf16 v[2:5], v[184:187], v[240:243], v[2:5]
	s_waitcnt vmcnt(16)
	ds_write_b128 v204, v[54:57] offset:0
	ds_write_b128 v204, v[62:65] offset:16384
	ds_write_b128 v204, v[66:69] offset:8192
	ds_write_b128 v204, v[70:73] offset:24576
	s_add_u32 s60, s6, 0xc80
	s_addc_u32 s61, s7, 0
	s_add_u32 s62, s54, 0xc80
	s_addc_u32 s63, s55, 0
	global_load_dwordx4 v[54:57], v150, s[60:61]
	global_load_dwordx4 v[62:65], v150, s[62:63]
	global_load_dwordx4 v[66:69], v152, s[60:61]
	global_load_dwordx4 v[70:73], v152, s[62:63]
	s_waitcnt lgkmcnt(0)
	s_barrier
	ds_read_b128 v[244:247], v106 offset:0
	ds_read_b128 v[248:251], v106 offset:1024
	ds_read_b128 v[180:183], v106 offset:2048
	ds_read_b128 v[184:187], v106 offset:3072
	ds_read_b128 v[212:215], v205 offset:0
	ds_read_b128 v[216:219], v205 offset:1024
	ds_read_b128 v[220:223], v205 offset:2048
	ds_read_b128 v[224:227], v205 offset:3072
	ds_read_b128 v[228:231], v205 offset:4096
	ds_read_b128 v[232:235], v205 offset:5120
	ds_read_b128 v[236:239], v205 offset:6144
	ds_read_b128 v[240:243], v205 offset:7168
	s_waitcnt lgkmcnt(0)
	v_mfma_f32_16x16x32_bf16 v[30:33], v[244:247], v[212:215], v[30:33]
	v_mfma_f32_16x16x32_bf16 v[26:29], v[180:183], v[212:215], v[26:29]
	v_mfma_f32_16x16x32_bf16 v[22:25], v[244:247], v[220:223], v[22:25]
	v_mfma_f32_16x16x32_bf16 v[18:21], v[180:183], v[220:223], v[18:21]
	v_mfma_f32_16x16x32_bf16 v[14:17], v[244:247], v[228:231], v[14:17]
	v_mfma_f32_16x16x32_bf16 v[10:13], v[180:183], v[228:231], v[10:13]
	v_mfma_f32_16x16x32_bf16 v[6:9], v[244:247], v[236:239], v[6:9]
	v_mfma_f32_16x16x32_bf16 v[2:5], v[180:183], v[236:239], v[2:5]
	v_mfma_f32_16x16x32_bf16 v[30:33], v[248:251], v[216:219], v[30:33]
	v_mfma_f32_16x16x32_bf16 v[26:29], v[184:187], v[216:219], v[26:29]
	v_mfma_f32_16x16x32_bf16 v[22:25], v[248:251], v[224:227], v[22:25]
	v_mfma_f32_16x16x32_bf16 v[18:21], v[184:187], v[224:227], v[18:21]
	v_mfma_f32_16x16x32_bf16 v[14:17], v[248:251], v[232:235], v[14:17]
	v_mfma_f32_16x16x32_bf16 v[10:13], v[184:187], v[232:235], v[10:13]
	v_mfma_f32_16x16x32_bf16 v[6:9], v[248:251], v[240:243], v[6:9]
	v_mfma_f32_16x16x32_bf16 v[2:5], v[184:187], v[240:243], v[2:5]
	s_waitcnt vmcnt(16)
	ds_write_b128 v204, v[74:77] offset:32768
	ds_write_b128 v204, v[78:81] offset:49152
	ds_write_b128 v204, v[82:85] offset:40960
	ds_write_b128 v204, v[86:89] offset:57344
	s_add_u32 s60, s6, 0xd00
	s_addc_u32 s61, s7, 0
	s_add_u32 s62, s54, 0xd00
	s_addc_u32 s63, s55, 0
	global_load_dwordx4 v[74:77], v150, s[60:61]
	global_load_dwordx4 v[78:81], v150, s[62:63]
	global_load_dwordx4 v[82:85], v152, s[60:61]
	global_load_dwordx4 v[86:89], v152, s[62:63]
	s_waitcnt lgkmcnt(0)
	s_barrier
	ds_read_b128 v[244:247], v106 offset:32768
	ds_read_b128 v[248:251], v106 offset:33792
	ds_read_b128 v[180:183], v106 offset:34816
	ds_read_b128 v[184:187], v106 offset:35840
	ds_read_b128 v[212:215], v205 offset:32768
	ds_read_b128 v[216:219], v205 offset:33792
	ds_read_b128 v[220:223], v205 offset:34816
	ds_read_b128 v[224:227], v205 offset:35840
	ds_read_b128 v[228:231], v205 offset:36864
	ds_read_b128 v[232:235], v205 offset:37888
	ds_read_b128 v[236:239], v205 offset:38912
	ds_read_b128 v[240:243], v205 offset:39936
	s_waitcnt lgkmcnt(0)
	v_mfma_f32_16x16x32_bf16 v[30:33], v[244:247], v[212:215], v[30:33]
	v_mfma_f32_16x16x32_bf16 v[26:29], v[180:183], v[212:215], v[26:29]
	v_mfma_f32_16x16x32_bf16 v[22:25], v[244:247], v[220:223], v[22:25]
	v_mfma_f32_16x16x32_bf16 v[18:21], v[180:183], v[220:223], v[18:21]
	v_mfma_f32_16x16x32_bf16 v[14:17], v[244:247], v[228:231], v[14:17]
	v_mfma_f32_16x16x32_bf16 v[10:13], v[180:183], v[228:231], v[10:13]
	v_mfma_f32_16x16x32_bf16 v[6:9], v[244:247], v[236:239], v[6:9]
	v_mfma_f32_16x16x32_bf16 v[2:5], v[180:183], v[236:239], v[2:5]
	v_mfma_f32_16x16x32_bf16 v[30:33], v[248:251], v[216:219], v[30:33]
	v_mfma_f32_16x16x32_bf16 v[26:29], v[184:187], v[216:219], v[26:29]
	v_mfma_f32_16x16x32_bf16 v[22:25], v[248:251], v[224:227], v[22:25]
	v_mfma_f32_16x16x32_bf16 v[18:21], v[184:187], v[224:227], v[18:21]
	v_mfma_f32_16x16x32_bf16 v[14:17], v[248:251], v[232:235], v[14:17]
	v_mfma_f32_16x16x32_bf16 v[10:13], v[184:187], v[232:235], v[10:13]
	v_mfma_f32_16x16x32_bf16 v[6:9], v[248:251], v[240:243], v[6:9]
	v_mfma_f32_16x16x32_bf16 v[2:5], v[184:187], v[240:243], v[2:5]
	s_waitcnt vmcnt(16)
	ds_write_b128 v204, v[90:93] offset:0
	ds_write_b128 v204, v[94:97] offset:16384
	ds_write_b128 v204, v[98:101] offset:8192
	ds_write_b128 v204, v[102:105] offset:24576
	s_add_u32 s60, s6, 0xd80
	s_addc_u32 s61, s7, 0
	s_add_u32 s62, s54, 0xd80
	s_addc_u32 s63, s55, 0
	global_load_dwordx4 v[90:93], v150, s[60:61]
	global_load_dwordx4 v[94:97], v150, s[62:63]
	global_load_dwordx4 v[98:101], v152, s[60:61]
	global_load_dwordx4 v[102:105], v152, s[62:63]
	s_waitcnt lgkmcnt(0)
	s_barrier
	ds_read_b128 v[244:247], v106 offset:0
	ds_read_b128 v[248:251], v106 offset:1024
	ds_read_b128 v[180:183], v106 offset:2048
	ds_read_b128 v[184:187], v106 offset:3072
	ds_read_b128 v[212:215], v205 offset:0
	ds_read_b128 v[216:219], v205 offset:1024
	ds_read_b128 v[220:223], v205 offset:2048
	ds_read_b128 v[224:227], v205 offset:3072
	ds_read_b128 v[228:231], v205 offset:4096
	ds_read_b128 v[232:235], v205 offset:5120
	ds_read_b128 v[236:239], v205 offset:6144
	ds_read_b128 v[240:243], v205 offset:7168
	s_waitcnt lgkmcnt(0)
	v_mfma_f32_16x16x32_bf16 v[30:33], v[244:247], v[212:215], v[30:33]
	v_mfma_f32_16x16x32_bf16 v[26:29], v[180:183], v[212:215], v[26:29]
	v_mfma_f32_16x16x32_bf16 v[22:25], v[244:247], v[220:223], v[22:25]
	v_mfma_f32_16x16x32_bf16 v[18:21], v[180:183], v[220:223], v[18:21]
	v_mfma_f32_16x16x32_bf16 v[14:17], v[244:247], v[228:231], v[14:17]
	v_mfma_f32_16x16x32_bf16 v[10:13], v[180:183], v[228:231], v[10:13]
	v_mfma_f32_16x16x32_bf16 v[6:9], v[244:247], v[236:239], v[6:9]
	v_mfma_f32_16x16x32_bf16 v[2:5], v[180:183], v[236:239], v[2:5]
	v_mfma_f32_16x16x32_bf16 v[30:33], v[248:251], v[216:219], v[30:33]
	v_mfma_f32_16x16x32_bf16 v[26:29], v[184:187], v[216:219], v[26:29]
	v_mfma_f32_16x16x32_bf16 v[22:25], v[248:251], v[224:227], v[22:25]
	v_mfma_f32_16x16x32_bf16 v[18:21], v[184:187], v[224:227], v[18:21]
	v_mfma_f32_16x16x32_bf16 v[14:17], v[248:251], v[232:235], v[14:17]
	v_mfma_f32_16x16x32_bf16 v[10:13], v[184:187], v[232:235], v[10:13]
	v_mfma_f32_16x16x32_bf16 v[6:9], v[248:251], v[240:243], v[6:9]
	v_mfma_f32_16x16x32_bf16 v[2:5], v[184:187], v[240:243], v[2:5]
	s_waitcnt vmcnt(16)
	ds_write_b128 v204, v[136:139] offset:32768
	ds_write_b128 v204, v[140:143] offset:49152
	ds_write_b128 v204, v[144:147] offset:40960
	ds_write_b128 v204, v[154:157] offset:57344
	s_add_u32 s60, s6, 0xe00
	s_addc_u32 s61, s7, 0
	s_add_u32 s62, s54, 0xe00
	s_addc_u32 s63, s55, 0
	global_load_dwordx4 v[136:139], v150, s[60:61]
	global_load_dwordx4 v[140:143], v150, s[62:63]
	global_load_dwordx4 v[144:147], v152, s[60:61]
	global_load_dwordx4 v[154:157], v152, s[62:63]
	s_waitcnt lgkmcnt(0)
	s_barrier
	ds_read_b128 v[244:247], v106 offset:32768
	ds_read_b128 v[248:251], v106 offset:33792
	ds_read_b128 v[180:183], v106 offset:34816
	ds_read_b128 v[184:187], v106 offset:35840
	ds_read_b128 v[212:215], v205 offset:32768
	ds_read_b128 v[216:219], v205 offset:33792
	ds_read_b128 v[220:223], v205 offset:34816
	ds_read_b128 v[224:227], v205 offset:35840
	ds_read_b128 v[228:231], v205 offset:36864
	ds_read_b128 v[232:235], v205 offset:37888
	ds_read_b128 v[236:239], v205 offset:38912
	ds_read_b128 v[240:243], v205 offset:39936
	s_waitcnt lgkmcnt(0)
	v_mfma_f32_16x16x32_bf16 v[30:33], v[244:247], v[212:215], v[30:33]
	v_mfma_f32_16x16x32_bf16 v[26:29], v[180:183], v[212:215], v[26:29]
	v_mfma_f32_16x16x32_bf16 v[22:25], v[244:247], v[220:223], v[22:25]
	v_mfma_f32_16x16x32_bf16 v[18:21], v[180:183], v[220:223], v[18:21]
	v_mfma_f32_16x16x32_bf16 v[14:17], v[244:247], v[228:231], v[14:17]
	v_mfma_f32_16x16x32_bf16 v[10:13], v[180:183], v[228:231], v[10:13]
	v_mfma_f32_16x16x32_bf16 v[6:9], v[244:247], v[236:239], v[6:9]
	v_mfma_f32_16x16x32_bf16 v[2:5], v[180:183], v[236:239], v[2:5]
	v_mfma_f32_16x16x32_bf16 v[30:33], v[248:251], v[216:219], v[30:33]
	v_mfma_f32_16x16x32_bf16 v[26:29], v[184:187], v[216:219], v[26:29]
	v_mfma_f32_16x16x32_bf16 v[22:25], v[248:251], v[224:227], v[22:25]
	v_mfma_f32_16x16x32_bf16 v[18:21], v[184:187], v[224:227], v[18:21]
	v_mfma_f32_16x16x32_bf16 v[14:17], v[248:251], v[232:235], v[14:17]
	v_mfma_f32_16x16x32_bf16 v[10:13], v[184:187], v[232:235], v[10:13]
	v_mfma_f32_16x16x32_bf16 v[6:9], v[248:251], v[240:243], v[6:9]
	v_mfma_f32_16x16x32_bf16 v[2:5], v[184:187], v[240:243], v[2:5]
	s_waitcnt vmcnt(16)
	ds_write_b128 v204, v[158:161] offset:0
	ds_write_b128 v204, v[162:165] offset:16384
	ds_write_b128 v204, v[166:169] offset:8192
	ds_write_b128 v204, v[176:179] offset:24576
	s_add_u32 s60, s6, 0xe80
	s_addc_u32 s61, s7, 0
	s_add_u32 s62, s54, 0xe80
	s_addc_u32 s63, s55, 0
	global_load_dwordx4 v[158:161], v150, s[60:61]
	global_load_dwordx4 v[162:165], v150, s[62:63]
	global_load_dwordx4 v[166:169], v152, s[60:61]
	global_load_dwordx4 v[176:179], v152, s[62:63]
	s_waitcnt lgkmcnt(0)
	s_barrier
	ds_read_b128 v[244:247], v106 offset:0
	ds_read_b128 v[248:251], v106 offset:1024
	ds_read_b128 v[180:183], v106 offset:2048
	ds_read_b128 v[184:187], v106 offset:3072
	ds_read_b128 v[212:215], v205 offset:0
	ds_read_b128 v[216:219], v205 offset:1024
	ds_read_b128 v[220:223], v205 offset:2048
	ds_read_b128 v[224:227], v205 offset:3072
	ds_read_b128 v[228:231], v205 offset:4096
	ds_read_b128 v[232:235], v205 offset:5120
	ds_read_b128 v[236:239], v205 offset:6144
	ds_read_b128 v[240:243], v205 offset:7168
	s_waitcnt lgkmcnt(0)
	v_mfma_f32_16x16x32_bf16 v[30:33], v[244:247], v[212:215], v[30:33]
	v_mfma_f32_16x16x32_bf16 v[26:29], v[180:183], v[212:215], v[26:29]
	v_mfma_f32_16x16x32_bf16 v[22:25], v[244:247], v[220:223], v[22:25]
	v_mfma_f32_16x16x32_bf16 v[18:21], v[180:183], v[220:223], v[18:21]
	v_mfma_f32_16x16x32_bf16 v[14:17], v[244:247], v[228:231], v[14:17]
	v_mfma_f32_16x16x32_bf16 v[10:13], v[180:183], v[228:231], v[10:13]
	v_mfma_f32_16x16x32_bf16 v[6:9], v[244:247], v[236:239], v[6:9]
	v_mfma_f32_16x16x32_bf16 v[2:5], v[180:183], v[236:239], v[2:5]
	v_mfma_f32_16x16x32_bf16 v[30:33], v[248:251], v[216:219], v[30:33]
	v_mfma_f32_16x16x32_bf16 v[26:29], v[184:187], v[216:219], v[26:29]
	v_mfma_f32_16x16x32_bf16 v[22:25], v[248:251], v[224:227], v[22:25]
	v_mfma_f32_16x16x32_bf16 v[18:21], v[184:187], v[224:227], v[18:21]
	v_mfma_f32_16x16x32_bf16 v[14:17], v[248:251], v[232:235], v[14:17]
	v_mfma_f32_16x16x32_bf16 v[10:13], v[184:187], v[232:235], v[10:13]
	v_mfma_f32_16x16x32_bf16 v[6:9], v[248:251], v[240:243], v[6:9]
	v_mfma_f32_16x16x32_bf16 v[2:5], v[184:187], v[240:243], v[2:5]
	s_waitcnt vmcnt(16)
	ds_write_b128 v204, v[54:57] offset:32768
	ds_write_b128 v204, v[62:65] offset:49152
	ds_write_b128 v204, v[66:69] offset:40960
	ds_write_b128 v204, v[70:73] offset:57344
	s_add_u32 s60, s6, 0xf00
	s_addc_u32 s61, s7, 0
	s_add_u32 s62, s54, 0xf00
	s_addc_u32 s63, s55, 0
	global_load_dwordx4 v[54:57], v150, s[60:61]
	global_load_dwordx4 v[62:65], v150, s[62:63]
	global_load_dwordx4 v[66:69], v152, s[60:61]
	global_load_dwordx4 v[70:73], v152, s[62:63]
	s_waitcnt lgkmcnt(0)
	s_barrier
	ds_read_b128 v[244:247], v106 offset:32768
	ds_read_b128 v[248:251], v106 offset:33792
	ds_read_b128 v[180:183], v106 offset:34816
	ds_read_b128 v[184:187], v106 offset:35840
	ds_read_b128 v[212:215], v205 offset:32768
	ds_read_b128 v[216:219], v205 offset:33792
	ds_read_b128 v[220:223], v205 offset:34816
	ds_read_b128 v[224:227], v205 offset:35840
	ds_read_b128 v[228:231], v205 offset:36864
	ds_read_b128 v[232:235], v205 offset:37888
	ds_read_b128 v[236:239], v205 offset:38912
	ds_read_b128 v[240:243], v205 offset:39936
	s_waitcnt lgkmcnt(0)
	v_mfma_f32_16x16x32_bf16 v[30:33], v[244:247], v[212:215], v[30:33]
	v_mfma_f32_16x16x32_bf16 v[26:29], v[180:183], v[212:215], v[26:29]
	v_mfma_f32_16x16x32_bf16 v[22:25], v[244:247], v[220:223], v[22:25]
	v_mfma_f32_16x16x32_bf16 v[18:21], v[180:183], v[220:223], v[18:21]
	v_mfma_f32_16x16x32_bf16 v[14:17], v[244:247], v[228:231], v[14:17]
	v_mfma_f32_16x16x32_bf16 v[10:13], v[180:183], v[228:231], v[10:13]
	v_mfma_f32_16x16x32_bf16 v[6:9], v[244:247], v[236:239], v[6:9]
	v_mfma_f32_16x16x32_bf16 v[2:5], v[180:183], v[236:239], v[2:5]
	v_mfma_f32_16x16x32_bf16 v[30:33], v[248:251], v[216:219], v[30:33]
	v_mfma_f32_16x16x32_bf16 v[26:29], v[184:187], v[216:219], v[26:29]
	v_mfma_f32_16x16x32_bf16 v[22:25], v[248:251], v[224:227], v[22:25]
	v_mfma_f32_16x16x32_bf16 v[18:21], v[184:187], v[224:227], v[18:21]
	v_mfma_f32_16x16x32_bf16 v[14:17], v[248:251], v[232:235], v[14:17]
	v_mfma_f32_16x16x32_bf16 v[10:13], v[184:187], v[232:235], v[10:13]
	v_mfma_f32_16x16x32_bf16 v[6:9], v[248:251], v[240:243], v[6:9]
	v_mfma_f32_16x16x32_bf16 v[2:5], v[184:187], v[240:243], v[2:5]
	s_waitcnt vmcnt(16)
	ds_write_b128 v204, v[74:77] offset:0
	ds_write_b128 v204, v[78:81] offset:16384
	ds_write_b128 v204, v[82:85] offset:8192
	ds_write_b128 v204, v[86:89] offset:24576
	s_add_u32 s60, s6, 0xf80
	s_addc_u32 s61, s7, 0
	s_add_u32 s62, s54, 0xf80
	s_addc_u32 s63, s55, 0
	global_load_dwordx4 v[74:77], v150, s[60:61]
	global_load_dwordx4 v[78:81], v150, s[62:63]
	global_load_dwordx4 v[82:85], v152, s[60:61]
	global_load_dwordx4 v[86:89], v152, s[62:63]
	s_waitcnt lgkmcnt(0)
	s_barrier
	ds_read_b128 v[244:247], v106 offset:0
	ds_read_b128 v[248:251], v106 offset:1024
	ds_read_b128 v[180:183], v106 offset:2048
	ds_read_b128 v[184:187], v106 offset:3072
	ds_read_b128 v[212:215], v205 offset:0
	ds_read_b128 v[216:219], v205 offset:1024
	ds_read_b128 v[220:223], v205 offset:2048
	ds_read_b128 v[224:227], v205 offset:3072
	ds_read_b128 v[228:231], v205 offset:4096
	ds_read_b128 v[232:235], v205 offset:5120
	ds_read_b128 v[236:239], v205 offset:6144
	ds_read_b128 v[240:243], v205 offset:7168
	s_waitcnt lgkmcnt(0)
	v_mfma_f32_16x16x32_bf16 v[30:33], v[244:247], v[212:215], v[30:33]
	v_mfma_f32_16x16x32_bf16 v[26:29], v[180:183], v[212:215], v[26:29]
	v_mfma_f32_16x16x32_bf16 v[22:25], v[244:247], v[220:223], v[22:25]
	v_mfma_f32_16x16x32_bf16 v[18:21], v[180:183], v[220:223], v[18:21]
	v_mfma_f32_16x16x32_bf16 v[14:17], v[244:247], v[228:231], v[14:17]
	v_mfma_f32_16x16x32_bf16 v[10:13], v[180:183], v[228:231], v[10:13]
	v_mfma_f32_16x16x32_bf16 v[6:9], v[244:247], v[236:239], v[6:9]
	v_mfma_f32_16x16x32_bf16 v[2:5], v[180:183], v[236:239], v[2:5]
	v_mfma_f32_16x16x32_bf16 v[30:33], v[248:251], v[216:219], v[30:33]
	v_mfma_f32_16x16x32_bf16 v[26:29], v[184:187], v[216:219], v[26:29]
	v_mfma_f32_16x16x32_bf16 v[22:25], v[248:251], v[224:227], v[22:25]
	v_mfma_f32_16x16x32_bf16 v[18:21], v[184:187], v[224:227], v[18:21]
	v_mfma_f32_16x16x32_bf16 v[14:17], v[248:251], v[232:235], v[14:17]
	v_mfma_f32_16x16x32_bf16 v[10:13], v[184:187], v[232:235], v[10:13]
	v_mfma_f32_16x16x32_bf16 v[6:9], v[248:251], v[240:243], v[6:9]
	v_mfma_f32_16x16x32_bf16 v[2:5], v[184:187], v[240:243], v[2:5]
	s_waitcnt vmcnt(16)
	ds_write_b128 v204, v[90:93] offset:32768
	ds_write_b128 v204, v[94:97] offset:49152
	ds_write_b128 v204, v[98:101] offset:40960
	ds_write_b128 v204, v[102:105] offset:57344
	s_waitcnt lgkmcnt(0)
	s_barrier
	ds_read_b128 v[244:247], v106 offset:32768
	ds_read_b128 v[248:251], v106 offset:33792
	ds_read_b128 v[180:183], v106 offset:34816
	ds_read_b128 v[184:187], v106 offset:35840
	ds_read_b128 v[212:215], v205 offset:32768
	ds_read_b128 v[216:219], v205 offset:33792
	ds_read_b128 v[220:223], v205 offset:34816
	ds_read_b128 v[224:227], v205 offset:35840
	ds_read_b128 v[228:231], v205 offset:36864
	ds_read_b128 v[232:235], v205 offset:37888
	ds_read_b128 v[236:239], v205 offset:38912
	ds_read_b128 v[240:243], v205 offset:39936
	s_waitcnt lgkmcnt(0)
	v_mfma_f32_16x16x32_bf16 v[30:33], v[244:247], v[212:215], v[30:33]
	v_mfma_f32_16x16x32_bf16 v[26:29], v[180:183], v[212:215], v[26:29]
	v_mfma_f32_16x16x32_bf16 v[22:25], v[244:247], v[220:223], v[22:25]
	v_mfma_f32_16x16x32_bf16 v[18:21], v[180:183], v[220:223], v[18:21]
	v_mfma_f32_16x16x32_bf16 v[14:17], v[244:247], v[228:231], v[14:17]
	v_mfma_f32_16x16x32_bf16 v[10:13], v[180:183], v[228:231], v[10:13]
	v_mfma_f32_16x16x32_bf16 v[6:9], v[244:247], v[236:239], v[6:9]
	v_mfma_f32_16x16x32_bf16 v[2:5], v[180:183], v[236:239], v[2:5]
	v_mfma_f32_16x16x32_bf16 v[30:33], v[248:251], v[216:219], v[30:33]
	v_mfma_f32_16x16x32_bf16 v[26:29], v[184:187], v[216:219], v[26:29]
	v_mfma_f32_16x16x32_bf16 v[22:25], v[248:251], v[224:227], v[22:25]
	v_mfma_f32_16x16x32_bf16 v[18:21], v[184:187], v[224:227], v[18:21]
	v_mfma_f32_16x16x32_bf16 v[14:17], v[248:251], v[232:235], v[14:17]
	v_mfma_f32_16x16x32_bf16 v[10:13], v[184:187], v[232:235], v[10:13]
	v_mfma_f32_16x16x32_bf16 v[6:9], v[248:251], v[240:243], v[6:9]
	v_mfma_f32_16x16x32_bf16 v[2:5], v[184:187], v[240:243], v[2:5]
	s_waitcnt vmcnt(12)
	ds_write_b128 v204, v[136:139] offset:0
	ds_write_b128 v204, v[140:143] offset:16384
	ds_write_b128 v204, v[144:147] offset:8192
	ds_write_b128 v204, v[154:157] offset:24576
	s_waitcnt lgkmcnt(0)
	s_barrier
	ds_read_b128 v[244:247], v106 offset:0
	ds_read_b128 v[248:251], v106 offset:1024
	ds_read_b128 v[180:183], v106 offset:2048
	ds_read_b128 v[184:187], v106 offset:3072
	ds_read_b128 v[212:215], v205 offset:0
	ds_read_b128 v[216:219], v205 offset:1024
	ds_read_b128 v[220:223], v205 offset:2048
	ds_read_b128 v[224:227], v205 offset:3072
	ds_read_b128 v[228:231], v205 offset:4096
	ds_read_b128 v[232:235], v205 offset:5120
	ds_read_b128 v[236:239], v205 offset:6144
	ds_read_b128 v[240:243], v205 offset:7168
	s_waitcnt lgkmcnt(0)
	v_mfma_f32_16x16x32_bf16 v[30:33], v[244:247], v[212:215], v[30:33]
	v_mfma_f32_16x16x32_bf16 v[26:29], v[180:183], v[212:215], v[26:29]
	v_mfma_f32_16x16x32_bf16 v[22:25], v[244:247], v[220:223], v[22:25]
	v_mfma_f32_16x16x32_bf16 v[18:21], v[180:183], v[220:223], v[18:21]
	v_mfma_f32_16x16x32_bf16 v[14:17], v[244:247], v[228:231], v[14:17]
	v_mfma_f32_16x16x32_bf16 v[10:13], v[180:183], v[228:231], v[10:13]
	v_mfma_f32_16x16x32_bf16 v[6:9], v[244:247], v[236:239], v[6:9]
	v_mfma_f32_16x16x32_bf16 v[2:5], v[180:183], v[236:239], v[2:5]
	v_mfma_f32_16x16x32_bf16 v[30:33], v[248:251], v[216:219], v[30:33]
	v_mfma_f32_16x16x32_bf16 v[26:29], v[184:187], v[216:219], v[26:29]
	v_mfma_f32_16x16x32_bf16 v[22:25], v[248:251], v[224:227], v[22:25]
	v_mfma_f32_16x16x32_bf16 v[18:21], v[184:187], v[224:227], v[18:21]
	v_mfma_f32_16x16x32_bf16 v[14:17], v[248:251], v[232:235], v[14:17]
	v_mfma_f32_16x16x32_bf16 v[10:13], v[184:187], v[232:235], v[10:13]
	v_mfma_f32_16x16x32_bf16 v[6:9], v[248:251], v[240:243], v[6:9]
	v_mfma_f32_16x16x32_bf16 v[2:5], v[184:187], v[240:243], v[2:5]
	s_waitcnt vmcnt(8)
	ds_write_b128 v204, v[158:161] offset:32768
	ds_write_b128 v204, v[162:165] offset:49152
	ds_write_b128 v204, v[166:169] offset:40960
	ds_write_b128 v204, v[176:179] offset:57344
	s_waitcnt lgkmcnt(0)
	s_barrier
	ds_read_b128 v[244:247], v106 offset:32768
	ds_read_b128 v[248:251], v106 offset:33792
	ds_read_b128 v[180:183], v106 offset:34816
	ds_read_b128 v[184:187], v106 offset:35840
	ds_read_b128 v[212:215], v205 offset:32768
	ds_read_b128 v[216:219], v205 offset:33792
	ds_read_b128 v[220:223], v205 offset:34816
	ds_read_b128 v[224:227], v205 offset:35840
	ds_read_b128 v[228:231], v205 offset:36864
	ds_read_b128 v[232:235], v205 offset:37888
	ds_read_b128 v[236:239], v205 offset:38912
	ds_read_b128 v[240:243], v205 offset:39936
	s_waitcnt lgkmcnt(0)
	v_mfma_f32_16x16x32_bf16 v[30:33], v[244:247], v[212:215], v[30:33]
	v_mfma_f32_16x16x32_bf16 v[26:29], v[180:183], v[212:215], v[26:29]
	v_mfma_f32_16x16x32_bf16 v[22:25], v[244:247], v[220:223], v[22:25]
	v_mfma_f32_16x16x32_bf16 v[18:21], v[180:183], v[220:223], v[18:21]
	v_mfma_f32_16x16x32_bf16 v[14:17], v[244:247], v[228:231], v[14:17]
	v_mfma_f32_16x16x32_bf16 v[10:13], v[180:183], v[228:231], v[10:13]
	v_mfma_f32_16x16x32_bf16 v[6:9], v[244:247], v[236:239], v[6:9]
	v_mfma_f32_16x16x32_bf16 v[2:5], v[180:183], v[236:239], v[2:5]
	v_mfma_f32_16x16x32_bf16 v[30:33], v[248:251], v[216:219], v[30:33]
	v_mfma_f32_16x16x32_bf16 v[26:29], v[184:187], v[216:219], v[26:29]
	v_mfma_f32_16x16x32_bf16 v[22:25], v[248:251], v[224:227], v[22:25]
	v_mfma_f32_16x16x32_bf16 v[18:21], v[184:187], v[224:227], v[18:21]
	v_mfma_f32_16x16x32_bf16 v[14:17], v[248:251], v[232:235], v[14:17]
	v_mfma_f32_16x16x32_bf16 v[10:13], v[184:187], v[232:235], v[10:13]
	v_mfma_f32_16x16x32_bf16 v[6:9], v[248:251], v[240:243], v[6:9]
	v_mfma_f32_16x16x32_bf16 v[2:5], v[184:187], v[240:243], v[2:5]
	s_waitcnt vmcnt(4)
	ds_write_b128 v204, v[54:57] offset:0
	ds_write_b128 v204, v[62:65] offset:16384
	ds_write_b128 v204, v[66:69] offset:8192
	ds_write_b128 v204, v[70:73] offset:24576
	s_waitcnt lgkmcnt(0)
	s_barrier
	ds_read_b128 v[244:247], v106 offset:0
	ds_read_b128 v[248:251], v106 offset:1024
	ds_read_b128 v[180:183], v106 offset:2048
	ds_read_b128 v[184:187], v106 offset:3072
	ds_read_b128 v[212:215], v205 offset:0
	ds_read_b128 v[216:219], v205 offset:1024
	ds_read_b128 v[220:223], v205 offset:2048
	ds_read_b128 v[224:227], v205 offset:3072
	ds_read_b128 v[228:231], v205 offset:4096
	ds_read_b128 v[232:235], v205 offset:5120
	ds_read_b128 v[236:239], v205 offset:6144
	ds_read_b128 v[240:243], v205 offset:7168
	s_waitcnt lgkmcnt(0)
	v_mfma_f32_16x16x32_bf16 v[30:33], v[244:247], v[212:215], v[30:33]
	v_mfma_f32_16x16x32_bf16 v[26:29], v[180:183], v[212:215], v[26:29]
	v_mfma_f32_16x16x32_bf16 v[22:25], v[244:247], v[220:223], v[22:25]
	v_mfma_f32_16x16x32_bf16 v[18:21], v[180:183], v[220:223], v[18:21]
	v_mfma_f32_16x16x32_bf16 v[14:17], v[244:247], v[228:231], v[14:17]
	v_mfma_f32_16x16x32_bf16 v[10:13], v[180:183], v[228:231], v[10:13]
	v_mfma_f32_16x16x32_bf16 v[6:9], v[244:247], v[236:239], v[6:9]
	v_mfma_f32_16x16x32_bf16 v[2:5], v[180:183], v[236:239], v[2:5]
	v_mfma_f32_16x16x32_bf16 v[30:33], v[248:251], v[216:219], v[30:33]
	v_mfma_f32_16x16x32_bf16 v[26:29], v[184:187], v[216:219], v[26:29]
	v_mfma_f32_16x16x32_bf16 v[22:25], v[248:251], v[224:227], v[22:25]
	v_mfma_f32_16x16x32_bf16 v[18:21], v[184:187], v[224:227], v[18:21]
	v_mfma_f32_16x16x32_bf16 v[14:17], v[248:251], v[232:235], v[14:17]
	v_mfma_f32_16x16x32_bf16 v[10:13], v[184:187], v[232:235], v[10:13]
	v_mfma_f32_16x16x32_bf16 v[6:9], v[248:251], v[240:243], v[6:9]
	v_mfma_f32_16x16x32_bf16 v[2:5], v[184:187], v[240:243], v[2:5]
	s_waitcnt vmcnt(0)
	ds_write_b128 v204, v[74:77] offset:32768
	ds_write_b128 v204, v[78:81] offset:49152
	ds_write_b128 v204, v[82:85] offset:40960
	ds_write_b128 v204, v[86:89] offset:57344
	s_waitcnt lgkmcnt(0)
	s_barrier
	ds_read_b128 v[244:247], v106 offset:32768
	ds_read_b128 v[248:251], v106 offset:33792
	ds_read_b128 v[180:183], v106 offset:34816
	ds_read_b128 v[184:187], v106 offset:35840
	ds_read_b128 v[212:215], v205 offset:32768
	ds_read_b128 v[216:219], v205 offset:33792
	ds_read_b128 v[220:223], v205 offset:34816
	ds_read_b128 v[224:227], v205 offset:35840
	ds_read_b128 v[228:231], v205 offset:36864
	ds_read_b128 v[232:235], v205 offset:37888
	ds_read_b128 v[236:239], v205 offset:38912
	ds_read_b128 v[240:243], v205 offset:39936
	s_waitcnt lgkmcnt(0)
	v_mfma_f32_16x16x32_bf16 v[30:33], v[244:247], v[212:215], v[30:33]
	v_mfma_f32_16x16x32_bf16 v[26:29], v[180:183], v[212:215], v[26:29]
	v_mfma_f32_16x16x32_bf16 v[22:25], v[244:247], v[220:223], v[22:25]
	v_mfma_f32_16x16x32_bf16 v[18:21], v[180:183], v[220:223], v[18:21]
	v_mfma_f32_16x16x32_bf16 v[14:17], v[244:247], v[228:231], v[14:17]
	v_mfma_f32_16x16x32_bf16 v[10:13], v[180:183], v[228:231], v[10:13]
	v_mfma_f32_16x16x32_bf16 v[6:9], v[244:247], v[236:239], v[6:9]
	v_mfma_f32_16x16x32_bf16 v[2:5], v[180:183], v[236:239], v[2:5]
	v_mfma_f32_16x16x32_bf16 v[30:33], v[248:251], v[216:219], v[30:33]
	v_mfma_f32_16x16x32_bf16 v[26:29], v[184:187], v[216:219], v[26:29]
	v_mfma_f32_16x16x32_bf16 v[22:25], v[248:251], v[224:227], v[22:25]
	v_mfma_f32_16x16x32_bf16 v[18:21], v[184:187], v[224:227], v[18:21]
	v_mfma_f32_16x16x32_bf16 v[14:17], v[248:251], v[232:235], v[14:17]
	v_mfma_f32_16x16x32_bf16 v[10:13], v[184:187], v[232:235], v[10:13]
	v_mfma_f32_16x16x32_bf16 v[6:9], v[248:251], v[240:243], v[6:9]
	v_mfma_f32_16x16x32_bf16 v[2:5], v[184:187], v[240:243], v[2:5]
	v_or_b32_e32 v56, s50, v59
	v_ashrrev_i32_e32 v57, 31, v56
	s_waitcnt vmcnt(0)
	s_barrier
	v_lshl_add_u64 v[54:55], v[56:57], 2, s[20:21]
	global_load_dwordx4 v[62:65], v[54:55], off
	v_lshlrev_b64 v[56:57], 1, v[56:57]
	v_lshl_add_u64 v[66:67], v[46:47], 0, v[56:57]
	s_add_i32 s1, s1, s96
	s_cmp_lt_i32 s1, 64
	s_waitcnt vmcnt(0)
	v_pk_add_f32 v[32:33], v[32:33], v[64:65]
	v_pk_add_f32 v[30:31], v[30:31], v[62:63]
	v_max_f32_e32 v63, 0, v33
	v_max_f32_e32 v62, 0, v31
	v_max_f32_e32 v30, 0, v30
	v_max_f32_e32 v31, 0, v32
	v_pk_mul_f32 v[32:33], v[62:63], v[62:63]
	v_pk_mul_f32 v[30:31], v[30:31], v[30:31]
	v_and_b32_sdwa v64, v33, v61 dst_sel:DWORD dst_unused:UNUSED_PAD src0_sel:WORD_1 src1_sel:DWORD
	v_and_b32_sdwa v65, v32, v61 dst_sel:DWORD dst_unused:UNUSED_PAD src0_sel:WORD_1 src1_sel:DWORD
	v_and_b32_sdwa v62, v31, v61 dst_sel:DWORD dst_unused:UNUSED_PAD src0_sel:WORD_1 src1_sel:DWORD
	v_and_b32_sdwa v63, v30, v61 dst_sel:DWORD dst_unused:UNUSED_PAD src0_sel:WORD_1 src1_sel:DWORD
	v_add3_u32 v33, v33, v64, s0
	v_add3_u32 v32, v32, v65, s0
	v_add3_u32 v30, v30, v63, s0
	v_add3_u32 v31, v31, v62, s0
	v_and_b32_e32 v33, 0xffff0000, v33
	v_and_b32_e32 v32, 0xffff0000, v32
	v_or_b32_sdwa v31, v33, v31 dst_sel:DWORD dst_unused:UNUSED_PAD src0_sel:DWORD src1_sel:WORD_1
	v_or_b32_sdwa v30, v32, v30 dst_sel:DWORD dst_unused:UNUSED_PAD src0_sel:DWORD src1_sel:WORD_1
	global_store_dwordx2 v[66:67], v[30:31], off
	global_load_dwordx4 v[30:33], v[54:55], off offset:64
	s_waitcnt vmcnt(0)
	v_pk_add_f32 v[28:29], v[28:29], v[32:33]
	v_pk_add_f32 v[26:27], v[26:27], v[30:31]
	v_max_f32_e32 v31, 0, v29
	v_max_f32_e32 v30, 0, v27
	v_max_f32_e32 v26, 0, v26
	v_max_f32_e32 v27, 0, v28
	v_pk_mul_f32 v[28:29], v[30:31], v[30:31]
	v_pk_mul_f32 v[26:27], v[26:27], v[26:27]
	v_and_b32_sdwa v32, v29, v61 dst_sel:DWORD dst_unused:UNUSED_PAD src0_sel:WORD_1 src1_sel:DWORD
	v_and_b32_sdwa v33, v28, v61 dst_sel:DWORD dst_unused:UNUSED_PAD src0_sel:WORD_1 src1_sel:DWORD
	v_and_b32_sdwa v30, v27, v61 dst_sel:DWORD dst_unused:UNUSED_PAD src0_sel:WORD_1 src1_sel:DWORD
	v_and_b32_sdwa v31, v26, v61 dst_sel:DWORD dst_unused:UNUSED_PAD src0_sel:WORD_1 src1_sel:DWORD
	v_add3_u32 v29, v29, v32, s0
	v_add3_u32 v28, v28, v33, s0
	v_add3_u32 v26, v26, v31, s0
	v_add3_u32 v27, v27, v30, s0
	v_and_b32_e32 v29, 0xffff0000, v29
	v_and_b32_e32 v28, 0xffff0000, v28
	v_or_b32_sdwa v27, v29, v27 dst_sel:DWORD dst_unused:UNUSED_PAD src0_sel:DWORD src1_sel:WORD_1
	v_or_b32_sdwa v26, v28, v26 dst_sel:DWORD dst_unused:UNUSED_PAD src0_sel:DWORD src1_sel:WORD_1
	global_store_dwordx2 v[66:67], v[26:27], off offset:32
	global_load_dwordx4 v[26:29], v[54:55], off
	v_lshl_add_u64 v[30:31], v[48:49], 0, v[56:57]
	s_waitcnt vmcnt(0)
	v_pk_add_f32 v[24:25], v[24:25], v[28:29]
	v_pk_add_f32 v[22:23], v[22:23], v[26:27]
	v_max_f32_e32 v27, 0, v25
	v_max_f32_e32 v26, 0, v23
	v_max_f32_e32 v22, 0, v22
	v_max_f32_e32 v23, 0, v24
	v_pk_mul_f32 v[24:25], v[26:27], v[26:27]
	v_pk_mul_f32 v[22:23], v[22:23], v[22:23]
	v_and_b32_sdwa v28, v25, v61 dst_sel:DWORD dst_unused:UNUSED_PAD src0_sel:WORD_1 src1_sel:DWORD
	v_and_b32_sdwa v29, v24, v61 dst_sel:DWORD dst_unused:UNUSED_PAD src0_sel:WORD_1 src1_sel:DWORD
	v_and_b32_sdwa v26, v23, v61 dst_sel:DWORD dst_unused:UNUSED_PAD src0_sel:WORD_1 src1_sel:DWORD
	v_and_b32_sdwa v27, v22, v61 dst_sel:DWORD dst_unused:UNUSED_PAD src0_sel:WORD_1 src1_sel:DWORD
	v_add3_u32 v25, v25, v28, s0
	v_add3_u32 v24, v24, v29, s0
	v_add3_u32 v22, v22, v27, s0
	v_add3_u32 v23, v23, v26, s0
	v_and_b32_e32 v25, 0xffff0000, v25
	v_and_b32_e32 v24, 0xffff0000, v24
	v_or_b32_sdwa v23, v25, v23 dst_sel:DWORD dst_unused:UNUSED_PAD src0_sel:DWORD src1_sel:WORD_1
	v_or_b32_sdwa v22, v24, v22 dst_sel:DWORD dst_unused:UNUSED_PAD src0_sel:DWORD src1_sel:WORD_1
	global_store_dwordx2 v[30:31], v[22:23], off
	global_load_dwordx4 v[22:25], v[54:55], off offset:64
	s_waitcnt vmcnt(0)
	v_pk_add_f32 v[20:21], v[20:21], v[24:25]
	v_pk_add_f32 v[18:19], v[18:19], v[22:23]
	v_max_f32_e32 v23, 0, v21
	v_max_f32_e32 v22, 0, v19
	v_max_f32_e32 v18, 0, v18
	v_max_f32_e32 v19, 0, v20
	v_pk_mul_f32 v[20:21], v[22:23], v[22:23]
	v_pk_mul_f32 v[18:19], v[18:19], v[18:19]
	v_and_b32_sdwa v24, v21, v61 dst_sel:DWORD dst_unused:UNUSED_PAD src0_sel:WORD_1 src1_sel:DWORD
	v_and_b32_sdwa v25, v20, v61 dst_sel:DWORD dst_unused:UNUSED_PAD src0_sel:WORD_1 src1_sel:DWORD
	v_and_b32_sdwa v22, v19, v61 dst_sel:DWORD dst_unused:UNUSED_PAD src0_sel:WORD_1 src1_sel:DWORD
	v_and_b32_sdwa v23, v18, v61 dst_sel:DWORD dst_unused:UNUSED_PAD src0_sel:WORD_1 src1_sel:DWORD
	v_add3_u32 v21, v21, v24, s0
	v_add3_u32 v20, v20, v25, s0
	v_add3_u32 v18, v18, v23, s0
	v_add3_u32 v19, v19, v22, s0
	v_and_b32_e32 v21, 0xffff0000, v21
	v_and_b32_e32 v20, 0xffff0000, v20
	v_or_b32_sdwa v19, v21, v19 dst_sel:DWORD dst_unused:UNUSED_PAD src0_sel:DWORD src1_sel:WORD_1
	v_or_b32_sdwa v18, v20, v18 dst_sel:DWORD dst_unused:UNUSED_PAD src0_sel:DWORD src1_sel:WORD_1
	global_store_dwordx2 v[30:31], v[18:19], off offset:32
	global_load_dwordx4 v[18:21], v[54:55], off
	v_lshl_add_u64 v[22:23], v[50:51], 0, v[56:57]
	s_waitcnt vmcnt(0)
	v_pk_add_f32 v[16:17], v[16:17], v[20:21]
	v_pk_add_f32 v[14:15], v[14:15], v[18:19]
	v_max_f32_e32 v19, 0, v17
	v_max_f32_e32 v18, 0, v15
	v_max_f32_e32 v14, 0, v14
	v_max_f32_e32 v15, 0, v16
	v_pk_mul_f32 v[16:17], v[18:19], v[18:19]
	v_pk_mul_f32 v[14:15], v[14:15], v[14:15]
	v_and_b32_sdwa v20, v17, v61 dst_sel:DWORD dst_unused:UNUSED_PAD src0_sel:WORD_1 src1_sel:DWORD
	v_and_b32_sdwa v21, v16, v61 dst_sel:DWORD dst_unused:UNUSED_PAD src0_sel:WORD_1 src1_sel:DWORD
	v_and_b32_sdwa v18, v15, v61 dst_sel:DWORD dst_unused:UNUSED_PAD src0_sel:WORD_1 src1_sel:DWORD
	v_and_b32_sdwa v19, v14, v61 dst_sel:DWORD dst_unused:UNUSED_PAD src0_sel:WORD_1 src1_sel:DWORD
	v_add3_u32 v17, v17, v20, s0
	v_add3_u32 v16, v16, v21, s0
	v_add3_u32 v14, v14, v19, s0
	v_add3_u32 v15, v15, v18, s0
	v_and_b32_e32 v17, 0xffff0000, v17
	v_and_b32_e32 v16, 0xffff0000, v16
	v_or_b32_sdwa v15, v17, v15 dst_sel:DWORD dst_unused:UNUSED_PAD src0_sel:DWORD src1_sel:WORD_1
	v_or_b32_sdwa v14, v16, v14 dst_sel:DWORD dst_unused:UNUSED_PAD src0_sel:DWORD src1_sel:WORD_1
	global_store_dwordx2 v[22:23], v[14:15], off
	global_load_dwordx4 v[14:17], v[54:55], off offset:64
	s_waitcnt vmcnt(0)
	v_pk_add_f32 v[12:13], v[12:13], v[16:17]
	v_pk_add_f32 v[10:11], v[10:11], v[14:15]
	v_max_f32_e32 v15, 0, v13
	v_max_f32_e32 v14, 0, v11
	v_max_f32_e32 v10, 0, v10
	v_max_f32_e32 v11, 0, v12
	v_pk_mul_f32 v[12:13], v[14:15], v[14:15]
	v_pk_mul_f32 v[10:11], v[10:11], v[10:11]
	v_and_b32_sdwa v16, v13, v61 dst_sel:DWORD dst_unused:UNUSED_PAD src0_sel:WORD_1 src1_sel:DWORD
	v_and_b32_sdwa v17, v12, v61 dst_sel:DWORD dst_unused:UNUSED_PAD src0_sel:WORD_1 src1_sel:DWORD
	v_and_b32_sdwa v14, v11, v61 dst_sel:DWORD dst_unused:UNUSED_PAD src0_sel:WORD_1 src1_sel:DWORD
	v_and_b32_sdwa v15, v10, v61 dst_sel:DWORD dst_unused:UNUSED_PAD src0_sel:WORD_1 src1_sel:DWORD
	v_add3_u32 v13, v13, v16, s0
	v_add3_u32 v12, v12, v17, s0
	v_add3_u32 v10, v10, v15, s0
	v_add3_u32 v11, v11, v14, s0
	v_and_b32_e32 v13, 0xffff0000, v13
	v_and_b32_e32 v12, 0xffff0000, v12
	v_or_b32_sdwa v11, v13, v11 dst_sel:DWORD dst_unused:UNUSED_PAD src0_sel:DWORD src1_sel:WORD_1
	v_or_b32_sdwa v10, v12, v10 dst_sel:DWORD dst_unused:UNUSED_PAD src0_sel:DWORD src1_sel:WORD_1
	global_store_dwordx2 v[22:23], v[10:11], off offset:32
	global_load_dwordx4 v[10:13], v[54:55], off
	v_lshl_add_u64 v[14:15], v[52:53], 0, v[56:57]
	s_waitcnt vmcnt(0)
	v_pk_add_f32 v[8:9], v[8:9], v[12:13]
	v_pk_add_f32 v[6:7], v[6:7], v[10:11]
	v_max_f32_e32 v11, 0, v9
	v_max_f32_e32 v10, 0, v7
	v_max_f32_e32 v6, 0, v6
	v_max_f32_e32 v7, 0, v8
	v_pk_mul_f32 v[8:9], v[10:11], v[10:11]
	v_pk_mul_f32 v[6:7], v[6:7], v[6:7]
	v_and_b32_sdwa v12, v9, v61 dst_sel:DWORD dst_unused:UNUSED_PAD src0_sel:WORD_1 src1_sel:DWORD
	v_and_b32_sdwa v13, v8, v61 dst_sel:DWORD dst_unused:UNUSED_PAD src0_sel:WORD_1 src1_sel:DWORD
	v_and_b32_sdwa v10, v7, v61 dst_sel:DWORD dst_unused:UNUSED_PAD src0_sel:WORD_1 src1_sel:DWORD
	v_and_b32_sdwa v11, v6, v61 dst_sel:DWORD dst_unused:UNUSED_PAD src0_sel:WORD_1 src1_sel:DWORD
	v_add3_u32 v9, v9, v12, s0
	v_add3_u32 v8, v8, v13, s0
	v_add3_u32 v6, v6, v11, s0
	v_add3_u32 v7, v7, v10, s0
	v_and_b32_e32 v9, 0xffff0000, v9
	v_and_b32_e32 v8, 0xffff0000, v8
	v_or_b32_sdwa v7, v9, v7 dst_sel:DWORD dst_unused:UNUSED_PAD src0_sel:DWORD src1_sel:WORD_1
	v_or_b32_sdwa v6, v8, v6 dst_sel:DWORD dst_unused:UNUSED_PAD src0_sel:DWORD src1_sel:WORD_1
	global_store_dwordx2 v[14:15], v[6:7], off
	global_load_dwordx4 v[6:9], v[54:55], off offset:64
	s_waitcnt vmcnt(0)
	v_pk_add_f32 v[4:5], v[4:5], v[8:9]
	v_pk_add_f32 v[2:3], v[2:3], v[6:7]
	v_max_f32_e32 v7, 0, v5
	v_max_f32_e32 v6, 0, v3
	v_max_f32_e32 v2, 0, v2
	v_max_f32_e32 v3, 0, v4
	v_pk_mul_f32 v[4:5], v[6:7], v[6:7]
	v_pk_mul_f32 v[2:3], v[2:3], v[2:3]
	v_and_b32_sdwa v8, v5, v61 dst_sel:DWORD dst_unused:UNUSED_PAD src0_sel:WORD_1 src1_sel:DWORD
	v_and_b32_sdwa v9, v4, v61 dst_sel:DWORD dst_unused:UNUSED_PAD src0_sel:WORD_1 src1_sel:DWORD
	v_and_b32_sdwa v6, v3, v61 dst_sel:DWORD dst_unused:UNUSED_PAD src0_sel:WORD_1 src1_sel:DWORD
	v_and_b32_sdwa v7, v2, v61 dst_sel:DWORD dst_unused:UNUSED_PAD src0_sel:WORD_1 src1_sel:DWORD
	v_add3_u32 v5, v5, v8, s0
	v_add3_u32 v4, v4, v9, s0
	v_add3_u32 v2, v2, v7, s0
	v_add3_u32 v3, v3, v6, s0
	v_and_b32_e32 v5, 0xffff0000, v5
	v_and_b32_e32 v4, 0xffff0000, v4
	v_or_b32_sdwa v3, v5, v3 dst_sel:DWORD dst_unused:UNUSED_PAD src0_sel:DWORD src1_sel:WORD_1
	v_or_b32_sdwa v2, v4, v2 dst_sel:DWORD dst_unused:UNUSED_PAD src0_sel:DWORD src1_sel:WORD_1
	global_store_dwordx2 v[14:15], v[2:3], off offset:32
	s_cbranch_scc1 .LBB0_841
